# adds lane-transposed epilogue for layer-0 down GEMM full tiles and one-tile-earlier K/V loads in the diff-attention map-0 core
# baseline (speedup 1.0000x reference)
.LBB0_796:
	s_xor_b64 s[6:7], s[0:1], -1
	s_lshl_b32 s0, s9, 3
	s_or_b32 s18, s0, 0x8000
	s_cmp_lg_u32 0, -1
	s_cselect_b32 s2, 0, 0
	s_or_b32 s12, s10, 64
	s_mov_b32 s13, s11
	v_lshl_add_u64 v[38:39], s[12:13], 0, v[144:145]
	v_mov_b64_e32 v[40:41], s[94:95]
	v_mad_u64_u32 v[40:41], s[0:1], v38, s60, v[40:41]
	v_mad_i32_i24 v41, v39, s60, v41
	v_mov_b32_e32 v33, v153
	v_lshl_add_u64 v[38:39], v[40:41], 0, v[32:33]
	v_lshl_add_u64 v[40:41], s[12:13], 0, v[146:147]
	v_mov_b64_e32 v[42:43], s[70:71]
	v_mad_u64_u32 v[42:43], s[0:1], v40, s60, v[42:43]
	v_mad_i32_i24 v43, v41, s60, v43
	v_xor_b32_e32 v64, 0x80000000, v36
	v_lshl_add_u64 v[40:41], v[42:43], 0, s[90:91]
	v_mov_b32_e32 v149, v153
	v_mov_b32_e32 v65, v64
	v_mov_b32_e32 v66, v64
	v_mov_b32_e32 v67, v64
	v_mov_b32_e32 v68, v64
	v_mov_b32_e32 v69, v64
	v_mov_b32_e32 v70, v64
	v_mov_b32_e32 v71, v64
	v_mov_b32_e32 v72, v64
	v_mov_b32_e32 v73, v64
	v_mov_b32_e32 v74, v64
	v_mov_b32_e32 v75, v64
	v_mov_b32_e32 v76, v64
	v_mov_b32_e32 v77, v64
	v_mov_b32_e32 v78, v64
	v_mov_b32_e32 v79, v64
	v_lshl_add_u64 v[46:47], v[40:41], 0, v[148:149]
	global_load_dwordx4 v[38:41], v[38:39], off offset:3072
	s_nop 0
	global_load_dwordx4 v[42:45], v[46:47], off
	v_add_co_u32_e32 v46, vcc, s58, v46
	v_sub_f32_e32 v0, v0, v36
	s_nop 0
	v_addc_co_u32_e32 v47, vcc, 0, v47, vcc
	global_load_dwordx4 v[46:49], v[46:47], off
	v_exp_f32_e32 v183, v0
	v_sub_f32_e32 v0, v1, v36
	v_exp_f32_e32 v168, v0
	v_sub_f32_e32 v0, v2, v36
	v_exp_f32_e32 v185, v0
	v_sub_f32_e32 v0, v3, v36
	v_exp_f32_e32 v166, v0
	v_sub_f32_e32 v0, v4, v36
	v_exp_f32_e32 v186, v0
	v_sub_f32_e32 v0, v5, v36
	v_exp_f32_e32 v172, v0
	v_sub_f32_e32 v0, v6, v36
	v_exp_f32_e32 v187, v0
	v_sub_f32_e32 v0, v7, v36
	v_exp_f32_e32 v170, v0
	v_sub_f32_e32 v0, v8, v36
	v_exp_f32_e32 v176, v0
	v_sub_f32_e32 v0, v9, v36
	v_exp_f32_e32 v177, v0
	v_sub_f32_e32 v0, v10, v36
	v_exp_f32_e32 v174, v0
	v_sub_f32_e32 v0, v11, v36
	v_exp_f32_e32 v175, v0
	v_sub_f32_e32 v0, v12, v36
	v_exp_f32_e32 v180, v0
	v_sub_f32_e32 v0, v13, v36
	v_and_b32_e32 v203, 63, v34
	v_exp_f32_e32 v181, v0
	v_sub_f32_e32 v0, v14, v36
	v_lshlrev_b32_e32 v37, 3, v203
	v_and_b32_e32 v35, 0xc0, v35
	v_lshlrev_b32_e32 v34, 1, v34
	v_exp_f32_e32 v178, v0
	v_sub_f32_e32 v0, v15, v36
	v_and_or_b32 v35, v37, 24, v35
	v_and_b32_e32 v34, 32, v34
	v_and_b32_e32 v37, 0x100, v37
	v_exp_f32_e32 v179, v0
	v_or3_b32 v34, v35, v34, v37
	v_add_u32_e32 v206, s2, v34
	s_addk_i32 s2, 0x4000
	v_mov_b32_e32 v204, 0
	v_sub_f32_e32 v95, v31, v36
	v_sub_f32_e32 v94, v30, v36
	v_sub_f32_e32 v93, v29, v36
	v_sub_f32_e32 v92, v28, v36
	v_sub_f32_e32 v91, v27, v36
	v_sub_f32_e32 v90, v26, v36
	v_sub_f32_e32 v89, v25, v36
	v_sub_f32_e32 v88, v24, v36
	v_sub_f32_e32 v87, v23, v36
	v_sub_f32_e32 v86, v22, v36
	v_sub_f32_e32 v85, v21, v36
	v_sub_f32_e32 v84, v20, v36
	v_sub_f32_e32 v83, v19, v36
	v_sub_f32_e32 v82, v18, v36
	v_sub_f32_e32 v81, v17, v36
	v_sub_f32_e32 v80, v16, v36
	s_waitcnt vmcnt(2)
	ds_write_b128 v209, v[38:41] offset:40960
	s_waitcnt vmcnt(1)
	ds_write_b128 v210, v[42:45] offset:16384
	s_waitcnt vmcnt(0)
	ds_write_b128 v211, v[46:49] offset:16384
	v_add_u32_e32 v205, s2, v34
	v_lshl_add_u64 v[150:151], s[94:95], 0, v[32:33]
	s_mov_b64 s[14:15], 0
	s_movk_i32 s9, 0x80
	s_mov_b32 s16, 2
	v_readfirstlane_b32 s100, v239
	s_add_i32 s48, s10, 0x80
	v_lshl_add_u64 v[244:245], s[48:49], 0, v[144:145]
	v_mad_u64_u32 v[246:247], s[0:1], v244, s60, v[150:151]
	v_mad_i32_i24 v247, v245, s60, v247
	v_lshl_add_u64 v[244:245], s[48:49], 0, v[146:147]
	v_mov_b64_e32 v[248:249], s[70:71]
	global_load_dwordx4 v[162:165], v[246:247], off offset:3072
	v_mad_u64_u32 v[246:247], s[0:1], v244, s60, v[248:249]
	v_mad_i32_i24 v247, v245, s60, v247
	s_mov_b32 s91, s49
	v_lshl_add_u64 v[244:245], v[246:247], 0, s[90:91]
	v_lshl_add_u64 v[244:245], v[244:245], 0, v[148:149]
	s_mov_b32 s0, s58
	s_mov_b32 s1, 0
	v_lshl_add_u64 v[246:247], v[244:245], 0, s[0:1]
	global_load_dwordx4 v[224:227], v[244:245], off
	global_load_dwordx4 v[232:235], v[246:247], off
	v_mov_b32_e32 v0, 0
	v_mov_b32_e32 v1, v204
	v_mov_b32_e32 v2, v204
	v_mov_b32_e32 v3, v204
	v_mov_b32_e32 v4, v204
	v_mov_b32_e32 v5, v204
	v_mov_b32_e32 v6, v204
	v_mov_b32_e32 v7, v204
	v_mov_b32_e32 v8, v204
	v_mov_b32_e32 v9, v204
	v_mov_b32_e32 v10, v204
	v_mov_b32_e32 v11, v204
	v_mov_b32_e32 v12, v204
	v_mov_b32_e32 v13, v204
	v_mov_b32_e32 v14, v204
	v_mov_b32_e32 v15, v204
	v_mov_b32_e32 v16, 0
	v_mov_b32_e32 v17, v204
	v_mov_b32_e32 v18, v204
	v_mov_b32_e32 v19, v204
	v_mov_b32_e32 v20, v204
	v_mov_b32_e32 v21, v204
	v_mov_b32_e32 v22, v204
	v_mov_b32_e32 v23, v204
	v_mov_b32_e32 v24, v204
	v_mov_b32_e32 v25, v204
	v_mov_b32_e32 v26, v204
	v_mov_b32_e32 v27, v204
	v_mov_b32_e32 v28, v204
	v_mov_b32_e32 v29, v204
	v_mov_b32_e32 v30, v204
	v_mov_b32_e32 v31, v204
	v_mov_b32_e32 v32, 0
	v_mov_b32_e32 v33, v204
	v_mov_b32_e32 v34, v204
	v_mov_b32_e32 v35, v204
	v_mov_b32_e32 v36, v204
	v_mov_b32_e32 v37, v204
	v_mov_b32_e32 v38, v204
	v_mov_b32_e32 v39, v204
	v_mov_b32_e32 v40, v204
	v_mov_b32_e32 v41, v204
	v_mov_b32_e32 v42, v204
	v_mov_b32_e32 v43, v204
	v_mov_b32_e32 v44, v204
	v_mov_b32_e32 v45, v204
	v_mov_b32_e32 v46, v204
	v_mov_b32_e32 v47, v204
	v_mov_b32_e32 v48, 0
	v_mov_b32_e32 v49, v204
	v_mov_b32_e32 v50, v204
	v_mov_b32_e32 v51, v204
	v_mov_b32_e32 v52, v204
	v_mov_b32_e32 v53, v204
	v_mov_b32_e32 v54, v204
	v_mov_b32_e32 v55, v204
	v_mov_b32_e32 v56, v204
	v_mov_b32_e32 v57, v204
	v_mov_b32_e32 v58, v204
	v_mov_b32_e32 v59, v204
	v_mov_b32_e32 v60, v204
	v_mov_b32_e32 v61, v204
	v_mov_b32_e32 v62, v204
	v_mov_b32_e32 v63, v204
	s_waitcnt lgkmcnt(0)
	s_barrier
.LBB0_797:
	ds_read_b128 v[188:191], v207 offset:45056
	ds_read_b128 v[112:115], v207 offset:40960
	v_exp_f32_e32 v152, v80
	v_exp_f32_e32 v167, v81
	v_exp_f32_e32 v169, v82
	v_exp_f32_e32 v171, v83
	s_waitcnt lgkmcnt(0)
	v_mfma_f32_32x32x16_bf16 v[96:111], v[112:115], v[140:143], v[64:79]
	v_exp_f32_e32 v173, v84
	v_add_f32_e32 v80, v183, v152
	v_add_f32_e32 v80, 0, v80
	v_add_f32_e32 v81, v168, v167
	v_add_f32_e32 v80, v81, v80
	v_add_f32_e32 v81, v185, v169
	v_add_f32_e32 v80, v81, v80
	v_mfma_f32_32x32x16_bf16 v[112:127], v[188:191], v[140:143], v[64:79]
	ds_read_b128 v[188:191], v208 offset:45056
	ds_read_b128 v[192:195], v208 offset:40960
	v_add_f32_e32 v81, v166, v171
	v_exp_f32_e32 v154, v88
	v_exp_f32_e32 v155, v89
	v_add_f32_e32 v80, v81, v80
	v_add_f32_e32 v81, v186, v173
	v_add_f32_e32 v80, v81, v80
	s_waitcnt lgkmcnt(1)
	v_mfma_f32_32x32x16_bf16 v[112:127], v[188:191], v[136:139], v[112:127]
	v_exp_f32_e32 v156, v90
	v_exp_f32_e32 v157, v91
	v_exp_f32_e32 v158, v92
	v_exp_f32_e32 v159, v93
	v_exp_f32_e32 v160, v94
	v_exp_f32_e32 v161, v95
	s_waitcnt lgkmcnt(0)
	v_mfma_f32_32x32x16_bf16 v[96:111], v[192:195], v[136:139], v[96:111]
	ds_read_b128 v[188:191], v213 offset:45056
	ds_read_b128 v[192:195], v213 offset:40960
	s_waitcnt lgkmcnt(1)
	v_mfma_f32_32x32x16_bf16 v[112:127], v[188:191], v[132:135], v[112:127]
	s_waitcnt lgkmcnt(0)
	v_mfma_f32_32x32x16_bf16 v[96:111], v[192:195], v[132:135], v[96:111]
	ds_read_b128 v[188:191], v212 offset:45056
	ds_read_b128 v[192:195], v212 offset:40960
	s_waitcnt lgkmcnt(1)
	v_mfma_f32_32x32x16_bf16 v[112:127], v[188:191], v[128:131], v[112:127]
	v_exp_f32_e32 v188, v85
	v_exp_f32_e32 v189, v86
	v_exp_f32_e32 v190, v87
	v_add_f32_e32 v81, v172, v188
	v_add_f32_e32 v80, v81, v80
	v_add_f32_e32 v81, v187, v189
	v_add_f32_e32 v80, v81, v80
	v_add_f32_e32 v81, v170, v190
	v_add_f32_e32 v82, v81, v80
	v_pk_add_f32 v[80:81], v[176:177], v[154:155]
	s_waitcnt lgkmcnt(0)
	v_mfma_f32_32x32x16_bf16 v[96:111], v[192:195], v[128:131], v[96:111]
	v_add_f32_e32 v80, v80, v82
	v_add_f32_e32 v82, v81, v80
	v_add_f32_e64 v80, v174, v156
	v_add_f32_e64 v81, v175, v157
	v_add_f32_e32 v80, v80, v82
	v_add_f32_e32 v82, v81, v80
	v_pk_add_f32 v[80:81], v[180:181], v[158:159]
	s_nop 0
	v_add_f32_e32 v80, v80, v82
	v_add_f32_e32 v82, v81, v80
	v_pk_add_f32 v[80:81], v[178:179], v[160:161]
	s_nop 0
	v_add_f32_e32 v80, v80, v82
	v_add_f32_e32 v182, v81, v80
	v_cvt_pk_bf16_f32 v80, v183, v168
	v_cvt_pk_bf16_f32 v81, v185, v166
	v_cvt_pk_bf16_f32 v82, v186, v172
	v_cvt_pk_bf16_f32 v83, v187, v170
	v_cvt_pk_bf16_f32 v84, v176, v177
	v_cvt_pk_bf16_f32 v85, v174, v175
	v_cvt_pk_bf16_f32 v86, v180, v181
	v_cvt_pk_bf16_f32 v87, v178, v179
	v_cvt_pk_bf16_f32 v88, v152, v167
	v_cvt_pk_bf16_f32 v89, v169, v171
	v_cvt_pk_bf16_f32 v90, v173, v188
	v_cvt_pk_bf16_f32 v91, v189, v190
	v_cvt_pk_bf16_f32 v92, v154, v155
	v_cvt_pk_bf16_f32 v93, v156, v157
	v_cvt_pk_bf16_f32 v94, v158, v159
	v_cvt_pk_bf16_f32 v95, v160, v161
	v_mov_b32_e32 v184, v182
	v_permlane32_swap_b32_e32 v80, v82
	v_permlane32_swap_b32_e32 v81, v83
	v_permlane32_swap_b32_e32 v84, v86
	v_permlane32_swap_b32_e32 v85, v87
	v_permlane32_swap_b32_e32 v88, v90
	v_permlane32_swap_b32_e32 v89, v91
	v_permlane32_swap_b32_e32 v92, v94
	v_permlane32_swap_b32_e32 v93, v95
	v_permlane32_swap_b32_e32 v182, v184
	s_add_i32 s0, s9, 64
	s_and_b32 s0, s0, 0x7c0
	s_cmp_lt_u32 s16, 31
	s_cselect_b32 s1, s10, s18
	s_add_i32 s48, s1, s0
	v_lshl_add_u64 v[154:155], s[48:49], 0, v[144:145]
	v_mad_u64_u32 v[156:157], s[0:1], v154, s60, v[150:151]
	v_mad_i32_i24 v157, v155, s60, v157
	v_lshl_add_u64 v[154:155], s[48:49], 0, v[146:147]
	v_mov_b64_e32 v[166:167], s[70:71]
	global_load_dwordx4 v[236:239], v[156:157], off offset:3072
	v_mad_u64_u32 v[156:157], s[0:1], v154, s60, v[166:167]
	v_mad_i32_i24 v157, v155, s60, v157
	s_mov_b32 s91, s49
	v_lshl_add_u64 v[154:155], v[156:157], 0, s[90:91]
	v_lshl_add_u64 v[154:155], v[154:155], 0, v[148:149]
	v_add_co_u32_e32 v156, vcc, s58, v154
	s_nop 1
	v_addc_co_u32_e32 v157, vcc, 0, v155, vcc
	global_load_dwordx4 v[244:247], v[154:155], off
	global_load_dwordx4 v[248:251], v[156:157], off
	ds_read_b64_tr_b16 v[168:169], v206 offset:0
	ds_read_b64_tr_b16 v[170:171], v206 offset:0x800
	ds_read_b64_tr_b16 v[172:173], v206 offset:0x1000
	ds_read_b64_tr_b16 v[174:175], v206 offset:0x1800
	ds_read_b64_tr_b16 v[176:177], v206 offset:0x2000
	ds_read_b64_tr_b16 v[178:179], v206 offset:0x2800
	ds_read_b64_tr_b16 v[190:191], v206 offset:0x3000
	ds_read_b64_tr_b16 v[192:193], v206 offset:0x3800
	s_waitcnt lgkmcnt(0)
	s_nop 0
	v_mfma_f32_32x32x16_bf16 v[48:63], v[80:83], v[168:171], v[48:63]
	v_exp_f32_e32 v154, v96
	v_exp_f32_e32 v168, v97
	ds_read_b64_tr_b16 v[96:97], v206 offset:0x200
	v_exp_f32_e32 v155, v98
	v_exp_f32_e32 v170, v99
	ds_read_b64_tr_b16 v[98:99], v206 offset:0xa00
	v_mfma_f32_32x32x16_bf16 v[48:63], v[84:87], v[172:175], v[48:63]
	ds_read_b64_tr_b16 v[172:173], v206 offset:0x1200
	ds_read_b64_tr_b16 v[174:175], v206 offset:0x1a00
	v_mfma_f32_32x32x16_bf16 v[48:63], v[88:91], v[176:179], v[48:63]
	ds_read_b64_tr_b16 v[176:177], v206 offset:0x2200
	ds_read_b64_tr_b16 v[178:179], v206 offset:0x2a00
	v_mfma_f32_32x32x16_bf16 v[48:63], v[92:95], v[190:193], v[48:63]
	ds_read_b64_tr_b16 v[190:191], v206 offset:0x3200
	ds_read_b64_tr_b16 v[192:193], v206 offset:0x3a00
	s_waitcnt lgkmcnt(0)
	v_mfma_f32_32x32x16_bf16 v[32:47], v[80:83], v[96:99], v[32:47]
	ds_read_b64_tr_b16 v[96:97], v206 offset:0x400
	ds_read_b64_tr_b16 v[98:99], v206 offset:0xc00
	v_exp_f32_e32 v156, v100
	v_exp_f32_e32 v157, v102
	v_mfma_f32_32x32x16_bf16 v[32:47], v[84:87], v[172:175], v[32:47]
	v_exp_f32_e32 v172, v101
	ds_read_b64_tr_b16 v[100:101], v206 offset:0x1400
	v_exp_f32_e32 v174, v103
	ds_read_b64_tr_b16 v[102:103], v206 offset:0x1c00
	v_mfma_f32_32x32x16_bf16 v[32:47], v[88:91], v[176:179], v[32:47]
	ds_read_b64_tr_b16 v[176:177], v206 offset:0x2400
	ds_read_b64_tr_b16 v[178:179], v206 offset:0x2c00
	v_mfma_f32_32x32x16_bf16 v[32:47], v[92:95], v[190:193], v[32:47]
	ds_read_b64_tr_b16 v[190:191], v206 offset:0x3400
	ds_read_b64_tr_b16 v[192:193], v206 offset:0x3c00
	s_waitcnt lgkmcnt(0)
	v_mfma_f32_32x32x16_bf16 v[16:31], v[80:83], v[96:99], v[16:31]
	ds_read_b64_tr_b16 v[96:97], v206 offset:0x600
	ds_read_b64_tr_b16 v[98:99], v206 offset:0xe00
	v_exp_f32_e32 v158, v104
	v_exp_f32_e32 v159, v106
	v_mfma_f32_32x32x16_bf16 v[16:31], v[84:87], v[100:103], v[16:31]
	ds_read_b64_tr_b16 v[100:101], v206 offset:0x1600
	ds_read_b64_tr_b16 v[102:103], v206 offset:0x1e00
	v_mfma_f32_32x32x16_bf16 v[16:31], v[88:91], v[176:179], v[16:31]
	v_exp_f32_e32 v176, v105
	ds_read_b64_tr_b16 v[104:105], v206 offset:0x2600
	v_exp_f32_e32 v178, v107
	ds_read_b64_tr_b16 v[106:107], v206 offset:0x2e00
	ds_read_b64_tr_b16 v[220:221], v206 offset:0x3600
	ds_read_b64_tr_b16 v[222:223], v206 offset:0x3e00
	s_waitcnt lgkmcnt(0)
	v_mfma_f32_32x32x16_bf16 v[16:31], v[92:95], v[190:193], v[16:31]
	v_mfma_f32_32x32x16_bf16 v[0:15], v[80:83], v[96:99], v[0:15]
	v_exp_f32_e32 v160, v108
	v_exp_f32_e32 v192, v109
	v_exp_f32_e32 v161, v110
	v_exp_f32_e32 v194, v111
	s_barrier
	v_mfma_f32_32x32x16_bf16 v[0:15], v[84:87], v[100:103], v[0:15]
	s_waitcnt vmcnt(5)
	ds_write_b128 v209, v[162:165] offset:32768
	s_waitcnt vmcnt(4)
	ds_write_b128 v210, v[224:227]
	s_waitcnt vmcnt(3)
	ds_write_b128 v211, v[232:235]
	s_waitcnt lgkmcnt(0)
	s_barrier
	v_mfma_f32_32x32x16_bf16 v[0:15], v[88:91], v[104:107], v[0:15]
	v_mfma_f32_32x32x16_bf16 v[0:15], v[92:95], v[220:223], v[0:15]
	ds_read_b128 v[186:189], v207 offset:36864
	ds_read_b128 v[80:83], v207 offset:32768
	v_exp_f32_e32 v215, v112
	v_exp_f32_e32 v152, v113
	v_exp_f32_e32 v216, v114
	v_exp_f32_e32 v217, v116
	s_waitcnt lgkmcnt(0)
	v_mfma_f32_32x32x16_bf16 v[96:111], v[80:83], v[140:143], v[64:79]
	v_add_f32_e32 v169, v154, v215
	v_add_f32_e64 v112, v168, v152
	v_add_f32_e64 v113, v169, v153
	v_add_f32_e32 v171, v155, v216
	v_pk_add_f32 v[112:113], v[112:113], v[112:113] op_sel_hi:[0,1]
	v_exp_f32_e32 v218, v118
	v_exp_f32_e32 v200, v119
	v_add_f32_e32 v173, v156, v217
	v_mfma_f32_32x32x16_bf16 v[80:95], v[186:189], v[140:143], v[64:79]
	ds_read_b128 v[186:189], v208 offset:36864
	ds_read_b128 v[196:199], v208 offset:32768
	v_exp_f32_e32 v219, v120
	v_exp_f32_e32 v180, v121
	v_add_f32_e32 v175, v157, v218
	v_exp_f32_e32 v220, v122
	v_add_f32_e32 v177, v158, v219
	v_exp_f32_e32 v221, v124
	s_waitcnt lgkmcnt(0)
	v_mfma_f32_32x32x16_bf16 v[96:111], v[196:199], v[136:139], v[96:111]
	v_add_f32_e32 v179, v159, v220
	v_exp_f32_e32 v222, v126
	v_exp_f32_e32 v190, v127
	v_add_f32_e32 v193, v160, v221
	v_add_f32_e32 v195, v161, v222
	v_mfma_f32_32x32x16_bf16 v[80:95], v[186:189], v[136:139], v[80:95]
	ds_read_b128 v[186:189], v213 offset:36864
	ds_read_b128 v[196:199], v213 offset:32768
	s_waitcnt lgkmcnt(0)
	v_mfma_f32_32x32x16_bf16 v[96:111], v[196:199], v[132:135], v[96:111]
	v_mfma_f32_32x32x16_bf16 v[80:95], v[186:189], v[132:135], v[80:95]
	ds_read_b128 v[186:189], v212 offset:36864
	ds_read_b128 v[196:199], v212 offset:32768
	s_waitcnt lgkmcnt(0)
	v_mfma_f32_32x32x16_bf16 v[96:111], v[196:199], v[128:131], v[96:111]
	v_exp_f32_e32 v196, v115
	v_exp_f32_e32 v198, v117
	v_mov_b32_e32 v197, v113
	v_pk_add_f32 v[112:113], v[170:171], v[196:197]
	s_nop 0
	v_pk_add_f32 v[112:113], v[112:113], v[112:113] op_sel_hi:[0,1]
	v_mov_b32_e32 v199, v113
	v_pk_add_f32 v[112:113], v[172:173], v[198:199]
	v_mfma_f32_32x32x16_bf16 v[80:95], v[186:189], v[128:131], v[80:95]
	v_pk_add_f32 v[112:113], v[112:113], v[112:113] op_sel_hi:[0,1]
	v_mov_b32_e32 v201, v113
	v_pk_add_f32 v[112:113], v[174:175], v[200:201]
	v_exp_f32_e32 v186, v123
	v_pk_add_f32 v[112:113], v[112:113], v[112:113] op_sel_hi:[0,1]
	v_mov_b32_e32 v181, v113
	v_pk_add_f32 v[112:113], v[176:177], v[180:181]
	v_exp_f32_e32 v188, v125
	v_pk_add_f32 v[112:113], v[112:113], v[112:113] op_sel_hi:[0,1]
	v_mov_b32_e32 v187, v113
	v_pk_add_f32 v[112:113], v[178:179], v[186:187]
	s_nop 0
	v_pk_add_f32 v[112:113], v[112:113], v[112:113] op_sel_hi:[0,1]
	v_mov_b32_e32 v189, v113
	v_pk_add_f32 v[112:113], v[192:193], v[188:189]
	s_nop 0
	v_pk_add_f32 v[112:113], v[112:113], v[112:113] op_sel_hi:[0,1]
	v_mov_b32_e32 v191, v113
	v_pk_add_f32 v[112:113], v[194:195], v[190:191]
	s_nop 0
	v_pk_add_f32 v[112:113], v[112:113], v[112:113] op_sel:[0,1] op_sel_hi:[1,0]
	s_nop 0
	v_mov_b32_e32 v185, v112
	s_nop 1
	v_permlane32_swap_b32_e32 v112, v185
	v_mov_b32_e32 v183, v112
	v_pk_add_f32 v[112:113], v[182:183], v[184:185]
	s_nop 0
	v_cmp_ngt_f32_e32 vcc, s59, v113
	v_cmp_ngt_f32_e64 s[0:1], s59, v112
	v_fma_f32 v114, v204, v214, v112
	s_or_b64 s[0:1], s[0:1], vcc
	v_add_f32_e32 v204, v114, v113
	s_or_b64 s[14:15], s[14:15], s[0:1]
	v_cvt_pk_bf16_f32 v112, v154, v168
	v_cvt_pk_bf16_f32 v113, v155, v170
	v_cvt_pk_bf16_f32 v114, v156, v172
	v_cvt_pk_bf16_f32 v115, v157, v174
	v_cvt_pk_bf16_f32 v116, v158, v176
	v_cvt_pk_bf16_f32 v117, v159, v178
	v_cvt_pk_bf16_f32 v118, v160, v192
	v_cvt_pk_bf16_f32 v119, v161, v194
	v_cvt_pk_bf16_f32 v120, v215, v152
	v_cvt_pk_bf16_f32 v121, v216, v196
	v_cvt_pk_bf16_f32 v122, v217, v198
	v_cvt_pk_bf16_f32 v123, v218, v200
	v_cvt_pk_bf16_f32 v124, v219, v180
	v_cvt_pk_bf16_f32 v125, v220, v186
	v_cvt_pk_bf16_f32 v126, v221, v188
	v_cvt_pk_bf16_f32 v127, v222, v190
	s_nop 0
	v_permlane32_swap_b32_e32 v112, v114
	v_permlane32_swap_b32_e32 v113, v115
	v_permlane32_swap_b32_e32 v116, v118
	v_permlane32_swap_b32_e32 v117, v119
	v_permlane32_swap_b32_e32 v120, v122
	v_permlane32_swap_b32_e32 v121, v123
	v_permlane32_swap_b32_e32 v124, v126
	v_permlane32_swap_b32_e32 v125, v127
	s_add_i32 s0, s16, -1
	s_cmp_lt_u32 s16, 30
	s_cselect_b32 s1, 0, 0xffffffe0
	s_cselect_b32 s17, s10, s18
	s_add_i32 s1, s1, s16
	s_lshl_b32 s1, s1, 6
	s_add_i32 s1, s1, s17
	s_add_i32 s48, s1, 0x80
	v_lshl_add_u64 v[154:155], s[48:49], 0, v[144:145]
	v_mad_u64_u32 v[156:157], s[22:23], v154, s60, v[150:151]
	v_mad_i32_i24 v157, v155, s60, v157
	v_lshl_add_u64 v[154:155], s[48:49], 0, v[146:147]
	global_load_dwordx4 v[162:165], v[156:157], off offset:3072
	v_mad_u64_u32 v[156:157], s[22:23], v154, s60, v[166:167]
	v_mad_i32_i24 v157, v155, s60, v157
	v_lshl_add_u64 v[154:155], v[156:157], 0, s[90:91]
	v_lshl_add_u64 v[154:155], v[154:155], 0, v[148:149]
	v_add_co_u32_e32 v156, vcc, s58, v154
	s_nop 1
	v_addc_co_u32_e32 v157, vcc, 0, v155, vcc
	global_load_dwordx4 v[224:227], v[154:155], off
	global_load_dwordx4 v[232:235], v[156:157], off
	ds_read_b64_tr_b16 v[166:167], v205 offset:0
	ds_read_b64_tr_b16 v[168:169], v205 offset:0x800
	ds_read_b64_tr_b16 v[170:171], v205 offset:0x1000
	ds_read_b64_tr_b16 v[172:173], v205 offset:0x1800
	ds_read_b64_tr_b16 v[174:175], v205 offset:0x2000
	ds_read_b64_tr_b16 v[176:177], v205 offset:0x2800
	ds_read_b64_tr_b16 v[178:179], v205 offset:0x3000
	ds_read_b64_tr_b16 v[180:181], v205 offset:0x3800
	s_waitcnt lgkmcnt(0)
	s_nop 0
	v_mfma_f32_32x32x16_bf16 v[48:63], v[112:115], v[166:169], v[48:63]
	v_exp_f32_e32 v183, v96
	v_exp_f32_e32 v168, v97
	ds_read_b64_tr_b16 v[96:97], v205 offset:0x200
	v_exp_f32_e32 v185, v98
	v_exp_f32_e32 v166, v99
	ds_read_b64_tr_b16 v[98:99], v205 offset:0xa00
	v_mfma_f32_32x32x16_bf16 v[48:63], v[116:119], v[170:173], v[48:63]
	ds_read_b64_tr_b16 v[170:171], v205 offset:0x1200
	ds_read_b64_tr_b16 v[172:173], v205 offset:0x1a00
	v_mfma_f32_32x32x16_bf16 v[48:63], v[120:123], v[174:177], v[48:63]
	ds_read_b64_tr_b16 v[174:175], v205 offset:0x2200
	ds_read_b64_tr_b16 v[176:177], v205 offset:0x2a00
	v_mfma_f32_32x32x16_bf16 v[48:63], v[124:127], v[178:181], v[48:63]
	ds_read_b64_tr_b16 v[178:179], v205 offset:0x3200
	ds_read_b64_tr_b16 v[180:181], v205 offset:0x3a00
	s_waitcnt lgkmcnt(0)
	v_mfma_f32_32x32x16_bf16 v[32:47], v[112:115], v[96:99], v[32:47]
	ds_read_b64_tr_b16 v[96:97], v205 offset:0x400
	ds_read_b64_tr_b16 v[98:99], v205 offset:0xc00
	v_exp_f32_e32 v186, v100
	v_exp_f32_e32 v187, v102
	v_mfma_f32_32x32x16_bf16 v[32:47], v[116:119], v[170:173], v[32:47]
	v_exp_f32_e32 v172, v101
	ds_read_b64_tr_b16 v[100:101], v205 offset:0x1400
	v_exp_f32_e32 v170, v103
	ds_read_b64_tr_b16 v[102:103], v205 offset:0x1c00
	v_mfma_f32_32x32x16_bf16 v[32:47], v[120:123], v[174:177], v[32:47]
	ds_read_b64_tr_b16 v[174:175], v205 offset:0x2400
	ds_read_b64_tr_b16 v[176:177], v205 offset:0x2c00
	v_mfma_f32_32x32x16_bf16 v[32:47], v[124:127], v[178:181], v[32:47]
	ds_read_b64_tr_b16 v[178:179], v205 offset:0x3400
	ds_read_b64_tr_b16 v[180:181], v205 offset:0x3c00
	s_waitcnt lgkmcnt(0)
	v_mfma_f32_32x32x16_bf16 v[16:31], v[112:115], v[96:99], v[16:31]
	ds_read_b64_tr_b16 v[96:97], v205 offset:0x600
	ds_read_b64_tr_b16 v[98:99], v205 offset:0xe00
	v_mfma_f32_32x32x16_bf16 v[16:31], v[116:119], v[100:103], v[16:31]
	ds_read_b64_tr_b16 v[100:101], v205 offset:0x1600
	ds_read_b64_tr_b16 v[102:103], v205 offset:0x1e00
	v_mfma_f32_32x32x16_bf16 v[16:31], v[120:123], v[174:177], v[16:31]
	v_exp_f32_e32 v176, v104
	v_exp_f32_e32 v177, v105
	ds_read_b64_tr_b16 v[104:105], v205 offset:0x2600
	v_exp_f32_e32 v174, v106
	v_exp_f32_e32 v175, v107
	ds_read_b64_tr_b16 v[106:107], v205 offset:0x2e00
	ds_read_b64_tr_b16 v[214:215], v205 offset:0x3600
	v_mfma_f32_32x32x16_bf16 v[16:31], v[124:127], v[178:181], v[16:31]
	ds_read_b64_tr_b16 v[216:217], v205 offset:0x3e00
	s_waitcnt lgkmcnt(0)
	v_mfma_f32_32x32x16_bf16 v[0:15], v[112:115], v[96:99], v[0:15]
	v_exp_f32_e32 v180, v108
	v_exp_f32_e32 v181, v109
	v_exp_f32_e32 v178, v110
	v_exp_f32_e32 v179, v111
	s_andn2_b64 s[2:3], s[2:3], exec
	s_and_b64 s[22:23], s[14:15], exec
	s_addk_i32 s9, 0x80
	v_mfma_f32_32x32x16_bf16 v[0:15], v[116:119], v[100:103], v[0:15]
	s_add_i32 s16, s16, 2
	s_or_b64 s[2:3], s[2:3], s[22:23]
	s_cmp_gt_u32 s0, 32
	s_barrier
	s_waitcnt vmcnt(5)
	ds_write_b128 v209, v[236:239] offset:40960
	s_waitcnt vmcnt(4)
	ds_write_b128 v210, v[244:247] offset:16384
	s_waitcnt vmcnt(3)
	ds_write_b128 v211, v[248:251] offset:16384
	v_mfma_f32_32x32x16_bf16 v[0:15], v[120:123], v[104:107], v[0:15]
	s_waitcnt lgkmcnt(0)
	s_barrier
	v_mfma_f32_32x32x16_bf16 v[0:15], v[124:127], v[214:217], v[0:15]
	v_mov_b32_e32 v214, 1.0
	s_cbranch_scc0 .LBB0_797
	v_mov_b32_e32 v239, s100
	ds_read_b128 v[112:115], v207 offset:45056
	ds_read_b128 v[116:119], v207 offset:40960
	v_exp_f32_e32 v152, v81
	v_exp_f32_e32 v124, v84
	v_exp_f32_e32 v84, v85
	v_exp_f32_e32 v125, v86
	s_waitcnt lgkmcnt(0)
	v_mfma_f32_32x32x16_bf16 v[96:111], v[116:119], v[140:143], v[64:79]
	v_exp_f32_e32 v86, v87
	v_add_f32_e32 v173, v186, v124
	v_exp_f32_e32 v126, v88
	v_add_f32_e32 v171, v187, v125
	v_exp_f32_e32 v127, v90
	v_exp_f32_e32 v120, v93
	v_exp_f32_e32 v122, v95
	v_mfma_f32_32x32x16_bf16 v[64:79], v[112:115], v[140:143], v[64:79]
	ds_read_b128 v[112:115], v208 offset:45056
	ds_read_b128 v[116:119], v208 offset:40960
	s_waitcnt lgkmcnt(1)
	v_mfma_f32_32x32x16_bf16 v[64:79], v[112:115], v[136:139], v[64:79]
	s_waitcnt lgkmcnt(0)
	v_mfma_f32_32x32x16_bf16 v[96:111], v[116:119], v[136:139], v[96:111]
	ds_read_b128 v[112:115], v213 offset:45056
	ds_read_b128 v[116:119], v213 offset:40960
	s_waitcnt lgkmcnt(1)
	v_mfma_f32_32x32x16_bf16 v[64:79], v[112:115], v[132:135], v[64:79]
	s_waitcnt lgkmcnt(0)
	v_mfma_f32_32x32x16_bf16 v[96:111], v[116:119], v[132:135], v[96:111]
	ds_read_b128 v[112:115], v212 offset:45056
	ds_read_b128 v[116:119], v212 offset:40960
	v_cvt_pk_bf16_f32 v88, v183, v168
	s_waitcnt lgkmcnt(1)
	v_mfma_f32_32x32x16_bf16 v[64:79], v[112:115], v[128:131], v[64:79]
	v_exp_f32_e32 v112, v80
	v_exp_f32_e32 v113, v82
	v_exp_f32_e32 v114, v83
	v_add_f32_e32 v83, v176, v126
	v_add_f32_e32 v169, v183, v112
	v_pk_add_f32 v[80:81], v[168:169], v[152:153]
	v_add_f32_e32 v167, v185, v113
	v_pk_add_f32 v[80:81], v[80:81], v[80:81] op_sel_hi:[0,1]
	v_mov_b32_e32 v115, v81
	v_pk_add_f32 v[80:81], v[166:167], v[114:115]
	s_waitcnt lgkmcnt(0)
	v_mfma_f32_32x32x16_bf16 v[96:111], v[116:119], v[128:131], v[96:111]
	v_pk_add_f32 v[80:81], v[80:81], v[80:81] op_sel_hi:[0,1]
	v_mov_b32_e32 v85, v81
	v_pk_add_f32 v[80:81], v[172:173], v[84:85]
	v_exp_f32_e32 v116, v89
	v_pk_add_f32 v[80:81], v[80:81], v[80:81] op_sel_hi:[0,1]
	v_mov_b32_e32 v87, v81
	v_pk_add_f32 v[80:81], v[170:171], v[86:87]
	v_exp_f32_e32 v118, v91
	v_pk_add_f32 v[80:81], v[80:81], v[80:81] op_sel_hi:[0,1]
	v_mov_b32_e32 v82, v177
	v_mov_b32_e32 v117, v81
	v_pk_add_f32 v[80:81], v[82:83], v[116:117]
	v_exp_f32_e32 v128, v92
	v_pk_add_f32 v[80:81], v[80:81], v[80:81] op_sel_hi:[0,1]
	v_add_f32_e32 v83, v174, v127
	v_mov_b32_e32 v82, v175
	v_mov_b32_e32 v119, v81
	v_pk_add_f32 v[80:81], v[82:83], v[118:119]
	v_exp_f32_e32 v129, v94
	v_pk_add_f32 v[80:81], v[80:81], v[80:81] op_sel_hi:[0,1]
	v_add_f32_e32 v83, v180, v128
	v_mov_b32_e32 v82, v181
	v_mov_b32_e32 v121, v81
	v_pk_add_f32 v[80:81], v[82:83], v[120:121]
	v_add_f32_e32 v83, v178, v129
	v_pk_add_f32 v[80:81], v[80:81], v[80:81] op_sel_hi:[0,1]
	v_mov_b32_e32 v82, v179
	v_mov_b32_e32 v123, v81
	v_pk_add_f32 v[80:81], v[82:83], v[122:123]
	v_cvt_pk_bf16_f32 v89, v185, v166
	v_cvt_pk_bf16_f32 v90, v186, v172
	v_cvt_pk_bf16_f32 v91, v187, v170
	v_cvt_pk_bf16_f32 v92, v176, v177
	v_cvt_pk_bf16_f32 v93, v174, v175
	s_nop 0
	v_pk_add_f32 v[80:81], v[80:81], v[80:81] op_sel:[0,1] op_sel_hi:[1,0]
	v_cvt_pk_bf16_f32 v94, v180, v181
	v_cvt_pk_bf16_f32 v95, v178, v179
	v_cvt_pk_bf16_f32 v112, v112, v152
	v_cvt_pk_bf16_f32 v113, v113, v114
	v_cvt_pk_bf16_f32 v114, v124, v84
	s_nop 0
	v_mov_b32_e32 v82, v80
	v_cvt_pk_bf16_f32 v115, v125, v86
	v_cvt_pk_bf16_f32 v116, v126, v116
	v_cvt_pk_bf16_f32 v117, v127, v118
	v_cvt_pk_bf16_f32 v118, v128, v120
	v_cvt_pk_bf16_f32 v119, v129, v122
	s_nop 1
	v_permlane32_swap_b32_e32 v80, v82
	v_permlane32_swap_b32_e32 v88, v90
	v_permlane32_swap_b32_e32 v89, v91
	v_permlane32_swap_b32_e32 v92, v94
	v_permlane32_swap_b32_e32 v93, v95
	v_permlane32_swap_b32_e32 v112, v114
	v_permlane32_swap_b32_e32 v113, v115
	v_permlane32_swap_b32_e32 v116, v118
	v_permlane32_swap_b32_e32 v117, v119
	ds_read_b64_tr_b16 v[84:85], v206 offset:0
	ds_read_b64_tr_b16 v[86:87], v206 offset:0x800
	ds_read_b64_tr_b16 v[120:121], v206 offset:0x1000
	ds_read_b64_tr_b16 v[122:123], v206 offset:0x1800
	ds_read_b64_tr_b16 v[124:125], v206 offset:0x2000
	ds_read_b64_tr_b16 v[126:127], v206 offset:0x2800
	ds_read_b64_tr_b16 v[128:129], v206 offset:0x3000
	ds_read_b64_tr_b16 v[130:131], v206 offset:0x3800
	s_waitcnt lgkmcnt(0)
	s_nop 0
	v_mfma_f32_32x32x16_bf16 v[48:63], v[88:91], v[84:87], v[48:63]
	v_exp_f32_e32 v132, v96
	v_exp_f32_e32 v84, v97
	ds_read_b64_tr_b16 v[96:97], v206 offset:0x200
	v_exp_f32_e32 v133, v98
	v_exp_f32_e32 v86, v99
	ds_read_b64_tr_b16 v[98:99], v206 offset:0xa00
	v_mfma_f32_32x32x16_bf16 v[48:63], v[92:95], v[120:123], v[48:63]
	ds_read_b64_tr_b16 v[120:121], v206 offset:0x1200
	ds_read_b64_tr_b16 v[122:123], v206 offset:0x1a00
	v_mfma_f32_32x32x16_bf16 v[48:63], v[112:115], v[124:127], v[48:63]
	ds_read_b64_tr_b16 v[124:125], v206 offset:0x2200
	ds_read_b64_tr_b16 v[126:127], v206 offset:0x2a00
	v_mfma_f32_32x32x16_bf16 v[48:63], v[116:119], v[128:131], v[48:63]
	ds_read_b64_tr_b16 v[128:129], v206 offset:0x3200
	ds_read_b64_tr_b16 v[130:131], v206 offset:0x3a00
	s_waitcnt lgkmcnt(0)
	v_mfma_f32_32x32x16_bf16 v[32:47], v[88:91], v[96:99], v[32:47]
	ds_read_b64_tr_b16 v[96:97], v206 offset:0x400
	ds_read_b64_tr_b16 v[98:99], v206 offset:0xc00
	v_exp_f32_e32 v134, v100
	v_exp_f32_e32 v135, v102
	v_mfma_f32_32x32x16_bf16 v[32:47], v[92:95], v[120:123], v[32:47]
	v_mfma_f32_32x32x16_bf16 v[32:47], v[112:115], v[124:127], v[32:47]
	v_mfma_f32_32x32x16_bf16 v[32:47], v[116:119], v[128:131], v[32:47]
	v_exp_f32_e32 v128, v101
	ds_read_b64_tr_b16 v[100:101], v206 offset:0x1400
	v_exp_f32_e32 v130, v103
	ds_read_b64_tr_b16 v[102:103], v206 offset:0x1c00
	ds_read_b64_tr_b16 v[120:121], v206 offset:0x2400
	ds_read_b64_tr_b16 v[122:123], v206 offset:0x2c00
	ds_read_b64_tr_b16 v[124:125], v206 offset:0x3400
	ds_read_b64_tr_b16 v[126:127], v206 offset:0x3c00
	s_waitcnt lgkmcnt(0)
	v_mfma_f32_32x32x16_bf16 v[16:31], v[88:91], v[96:99], v[16:31]
	ds_read_b64_tr_b16 v[96:97], v206 offset:0x600
	ds_read_b64_tr_b16 v[98:99], v206 offset:0xe00
	v_exp_f32_e32 v136, v104
	v_exp_f32_e32 v137, v106
	v_mfma_f32_32x32x16_bf16 v[16:31], v[92:95], v[100:103], v[16:31]
	ds_read_b64_tr_b16 v[100:101], v206 offset:0x1600
	ds_read_b64_tr_b16 v[102:103], v206 offset:0x1e00
	v_mfma_f32_32x32x16_bf16 v[16:31], v[112:115], v[120:123], v[16:31]
	v_mfma_f32_32x32x16_bf16 v[16:31], v[116:119], v[124:127], v[16:31]
	v_exp_f32_e32 v124, v105
	ds_read_b64_tr_b16 v[104:105], v206 offset:0x2600
	v_exp_f32_e32 v126, v107
	ds_read_b64_tr_b16 v[106:107], v206 offset:0x2e00
	ds_read_b64_tr_b16 v[120:121], v206 offset:0x3600
	ds_read_b64_tr_b16 v[122:123], v206 offset:0x3e00
	s_waitcnt lgkmcnt(0)
	v_mfma_f32_32x32x16_bf16 v[0:15], v[88:91], v[96:99], v[0:15]
	v_exp_f32_e32 v152, v65
	v_exp_f32_e32 v88, v109
	v_exp_f32_e32 v109, v66
	v_exp_f32_e32 v90, v111
	v_exp_f32_e32 v111, v70
	v_exp_f32_e32 v96, v71
	v_add_f32_e32 v87, v133, v109
	v_mfma_f32_32x32x16_bf16 v[0:15], v[92:95], v[100:103], v[0:15]
	v_exp_f32_e32 v92, v67
	v_exp_f32_e32 v94, v69
	v_exp_f32_e32 v98, v73
	v_add_f32_e32 v131, v135, v111
	v_exp_f32_e32 v100, v75
	v_exp_f32_e32 v102, v77
	v_cvt_pk_bf16_f32 v66, v132, v84
	v_mfma_f32_32x32x16_bf16 v[0:15], v[112:115], v[104:107], v[0:15]
	v_exp_f32_e32 v106, v108
	v_exp_f32_e32 v108, v64
	v_exp_f32_e32 v107, v110
	v_exp_f32_e32 v110, v68
	v_exp_f32_e32 v112, v72
	v_add_f32_e32 v85, v132, v108
	v_pk_add_f32 v[64:65], v[84:85], v[152:153]
	v_add_f32_e32 v129, v134, v110
	v_pk_add_f32 v[64:65], v[64:65], v[64:65] op_sel_hi:[0,1]
	v_mov_b32_e32 v93, v65
	v_pk_add_f32 v[64:65], v[86:87], v[92:93]
	v_exp_f32_e32 v113, v74
	v_pk_add_f32 v[64:65], v[64:65], v[64:65] op_sel_hi:[0,1]
	v_mov_b32_e32 v95, v65
	v_pk_add_f32 v[64:65], v[128:129], v[94:95]
	v_add_f32_e32 v125, v136, v112
	v_pk_add_f32 v[64:65], v[64:65], v[64:65] op_sel_hi:[0,1]
	v_mov_b32_e32 v97, v65
	v_pk_add_f32 v[64:65], v[130:131], v[96:97]
	v_exp_f32_e32 v114, v76
	v_pk_add_f32 v[64:65], v[64:65], v[64:65] op_sel_hi:[0,1]
	v_mov_b32_e32 v99, v65
	v_pk_add_f32 v[64:65], v[124:125], v[98:99]
	v_add_f32_e32 v127, v137, v113
	v_pk_add_f32 v[64:65], v[64:65], v[64:65] op_sel_hi:[0,1]
	v_mov_b32_e32 v101, v65
	v_pk_add_f32 v[64:65], v[126:127], v[100:101]
	v_exp_f32_e32 v115, v78
	v_pk_add_f32 v[64:65], v[64:65], v[64:65] op_sel_hi:[0,1]
	v_exp_f32_e32 v104, v79
	v_add_f32_e32 v89, v106, v114
	v_mov_b32_e32 v103, v65
	v_pk_add_f32 v[64:65], v[88:89], v[102:103]
	v_add_f32_e32 v91, v107, v115
	v_pk_add_f32 v[64:65], v[64:65], v[64:65] op_sel_hi:[0,1]
	v_mov_b32_e32 v105, v65
	v_pk_add_f32 v[64:65], v[90:91], v[104:105]
	v_mfma_f32_32x32x16_bf16 v[0:15], v[116:119], v[120:123], v[0:15]
	v_pk_add_f32 v[64:65], v[64:65], v[64:65] op_sel:[0,1] op_sel_hi:[1,0]
	v_cvt_pk_bf16_f32 v67, v133, v86
	v_cvt_pk_bf16_f32 v68, v134, v128
	v_cvt_pk_bf16_f32 v69, v135, v130
	v_cvt_pk_bf16_f32 v70, v136, v124
	v_cvt_pk_bf16_f32 v71, v137, v126
	s_nop 0
	v_mov_b32_e32 v83, v64
	s_nop 1
	v_permlane32_swap_b32_e32 v64, v83
	v_mov_b32_e32 v81, v64
	v_pk_add_f32 v[64:65], v[80:81], v[82:83]
	v_cvt_pk_bf16_f32 v72, v106, v88
	v_cvt_pk_bf16_f32 v73, v107, v90
	v_cvt_pk_bf16_f32 v74, v108, v152
	v_cvt_pk_bf16_f32 v75, v109, v92
	v_cvt_pk_bf16_f32 v76, v110, v94
	s_nop 0
	v_cmp_ngt_f32_e32 vcc, s59, v65
	v_cmp_ngt_f32_e64 s[0:1], s59, v64
	s_or_b64 s[0:1], s[0:1], vcc
	s_or_b64 s[0:1], s[2:3], s[0:1]
	v_cvt_pk_bf16_f32 v77, v111, v96
	v_cvt_pk_bf16_f32 v78, v112, v98
	v_cvt_pk_bf16_f32 v79, v113, v100
	v_cvt_pk_bf16_f32 v80, v114, v102
	v_cvt_pk_bf16_f32 v81, v115, v104
	v_permlane32_swap_b32_e32 v66, v68
	v_permlane32_swap_b32_e32 v67, v69
	v_permlane32_swap_b32_e32 v70, v72
	v_permlane32_swap_b32_e32 v71, v73
	v_permlane32_swap_b32_e32 v74, v76
	v_permlane32_swap_b32_e32 v75, v77
	v_permlane32_swap_b32_e32 v78, v80
	v_permlane32_swap_b32_e32 v79, v81
	ds_read_b64_tr_b16 v[82:83], v205 offset:0
	ds_read_b64_tr_b16 v[84:85], v205 offset:0x800
	ds_read_b64_tr_b16 v[86:87], v205 offset:0x1000
	ds_read_b64_tr_b16 v[88:89], v205 offset:0x1800
	ds_read_b64_tr_b16 v[90:91], v205 offset:0x2000
	ds_read_b64_tr_b16 v[92:93], v205 offset:0x2800
	ds_read_b64_tr_b16 v[94:95], v205 offset:0x3000
	ds_read_b64_tr_b16 v[96:97], v205 offset:0x3800
	s_waitcnt lgkmcnt(0)
	s_nop 0
	v_mfma_f32_32x32x16_bf16 v[48:63], v[66:69], v[82:85], v[48:63]
	ds_read_b64_tr_b16 v[82:83], v205 offset:0x200
	ds_read_b64_tr_b16 v[84:85], v205 offset:0xa00
	v_mfma_f32_32x32x16_bf16 v[48:63], v[70:73], v[86:89], v[48:63]
	ds_read_b64_tr_b16 v[86:87], v205 offset:0x1200
	ds_read_b64_tr_b16 v[88:89], v205 offset:0x1a00
	v_mfma_f32_32x32x16_bf16 v[48:63], v[74:77], v[90:93], v[48:63]
	ds_read_b64_tr_b16 v[90:91], v205 offset:0x2200
	ds_read_b64_tr_b16 v[92:93], v205 offset:0x2a00
	v_mfma_f32_32x32x16_bf16 v[48:63], v[78:81], v[94:97], v[48:63]
	ds_read_b64_tr_b16 v[94:95], v205 offset:0x3200
	ds_read_b64_tr_b16 v[96:97], v205 offset:0x3a00
	s_waitcnt lgkmcnt(0)
	v_mfma_f32_32x32x16_bf16 v[32:47], v[66:69], v[82:85], v[32:47]
	ds_read_b64_tr_b16 v[82:83], v205 offset:0x400
	ds_read_b64_tr_b16 v[84:85], v205 offset:0xc00
	v_mfma_f32_32x32x16_bf16 v[32:47], v[70:73], v[86:89], v[32:47]
	ds_read_b64_tr_b16 v[86:87], v205 offset:0x1400
	ds_read_b64_tr_b16 v[88:89], v205 offset:0x1c00
	v_mfma_f32_32x32x16_bf16 v[32:47], v[74:77], v[90:93], v[32:47]
	ds_read_b64_tr_b16 v[90:91], v205 offset:0x2400
	ds_read_b64_tr_b16 v[92:93], v205 offset:0x2c00
	v_mfma_f32_32x32x16_bf16 v[32:47], v[78:81], v[94:97], v[32:47]
	ds_read_b64_tr_b16 v[94:95], v205 offset:0x3400
	ds_read_b64_tr_b16 v[96:97], v205 offset:0x3c00
	s_waitcnt lgkmcnt(0)
	v_mfma_f32_32x32x16_bf16 v[16:31], v[66:69], v[82:85], v[16:31]
	ds_read_b64_tr_b16 v[82:83], v205 offset:0x600
	ds_read_b64_tr_b16 v[84:85], v205 offset:0xe00
	v_mfma_f32_32x32x16_bf16 v[16:31], v[70:73], v[86:89], v[16:31]
	ds_read_b64_tr_b16 v[86:87], v205 offset:0x1600
	ds_read_b64_tr_b16 v[88:89], v205 offset:0x1e00
	v_mfma_f32_32x32x16_bf16 v[16:31], v[74:77], v[90:93], v[16:31]
	ds_read_b64_tr_b16 v[90:91], v205 offset:0x2600
	ds_read_b64_tr_b16 v[92:93], v205 offset:0x2e00
	v_mfma_f32_32x32x16_bf16 v[16:31], v[78:81], v[94:97], v[16:31]
	ds_read_b64_tr_b16 v[94:95], v205 offset:0x3600
	ds_read_b64_tr_b16 v[96:97], v205 offset:0x3e00
	s_waitcnt lgkmcnt(0)
	v_mfma_f32_32x32x16_bf16 v[0:15], v[66:69], v[82:85], v[0:15]
	v_mfma_f32_32x32x16_bf16 v[0:15], v[70:73], v[86:89], v[0:15]
	v_mfma_f32_32x32x16_bf16 v[0:15], v[74:77], v[90:93], v[0:15]
	v_mfma_f32_32x32x16_bf16 v[0:15], v[78:81], v[94:97], v[0:15]
	s_setprio 0
	v_cndmask_b32_e64 v66, 0, 1, s[0:1]
	v_cmp_ne_u32_e32 vcc, 0, v66
	s_cmp_lg_u64 vcc, 0
	s_cselect_b64 s[0:1], -1, 0
	v_cmp_eq_u32_e32 vcc, 0, v203
	s_and_b64 s[2:3], vcc, s[0:1]
	s_and_saveexec_b64 s[0:1], s[2:3]
	ds_write_b32 v153, v229 offset:51200
	s_or_b64 exec, exec, s[0:1]
	s_waitcnt vmcnt(0) lgkmcnt(0)
	s_barrier
	ds_read_b32 v66, v153 offset:51200
	s_mov_b32 s9, s49
	s_waitcnt lgkmcnt(0)
	s_barrier
	v_cmp_eq_u32_e32 vcc, 0, v66
	s_cbranch_vccnz .LBB0_824
	v_mbcnt_lo_u32_b32 v0, -1, 0
	v_mbcnt_hi_u32_b32 v0, -1, v0
	v_mov_b64_e32 v[14:15], s[94:95]
	v_add_u32_e32 v35, s33, v0
	v_mov_b32_e32 v33, v153
	v_ashrrev_i32_e32 v0, 1, v35
	v_and_b32_e32 v34, 31, v35
	v_and_b32_e32 v0, 0xffffffe0, v0
	v_ashrrev_i32_e32 v1, 31, v0
	v_or_b32_e32 v152, s8, v34
	v_ashrrev_i32_e32 v148, 3, v35
	v_lshlrev_b32_e32 v16, 3, v35
	v_lshl_add_u64 v[12:13], v[152:153], 0, v[0:1]
	v_and_b32_e32 v0, 56, v16
	v_ashrrev_i32_e32 v149, 31, v148
	v_lshlrev_b32_e32 v32, 1, v0
	v_lshl_add_u64 v[0:1], v[148:149], 0, s[10:11]
	v_ashrrev_i32_e32 v150, 4, v35
	v_mad_u64_u32 v[2:3], s[0:1], v0, s60, v[14:15]
	v_mad_i32_i24 v3, v1, s60, v3
	v_ashrrev_i32_e32 v151, 31, v150
	v_lshl_add_u64 v[0:1], v[2:3], 0, v[32:33]
	v_lshl_add_u64 v[2:3], v[150:151], 0, s[10:11]
	v_mov_b64_e32 v[4:5], s[70:71]
	v_mad_u64_u32 v[4:5], s[0:1], v2, s60, v[4:5]
	v_and_b32_e32 v6, 0x78, v16
	v_mad_i32_i24 v5, v3, s60, v5
	s_mov_b32 s91, s49
	v_lshl_add_u64 v[2:3], v[4:5], 0, s[90:91]
	v_lshlrev_b32_e32 v152, 1, v6
	v_lshl_add_u64 v[8:9], v[2:3], 0, v[152:153]
	global_load_dwordx4 v[0:3], v[0:1], off offset:3072
	s_nop 0
	global_load_dwordx4 v[4:7], v[8:9], off
	v_add_co_u32_e32 v8, vcc, s58, v8
	v_mad_u64_u32 v[14:15], s[0:1], v12, s60, v[14:15]
	s_nop 0
	v_addc_co_u32_e32 v9, vcc, 0, v9, vcc
	global_load_dwordx4 v[8:11], v[8:9], off
	v_lshrrev_b32_e32 v17, 1, v35
	v_mad_i32_i24 v15, v13, s60, v15
	v_and_b32_e32 v146, 16, v17
	v_mov_b32_e32 v147, v153
	v_lshl_add_u64 v[12:13], v[14:15], 0, v[146:147]
	global_load_dwordx4 v[116:119], v[12:13], off offset:2048
	global_load_dwordx4 v[120:123], v[12:13], off offset:2080
	global_load_dwordx4 v[124:127], v[12:13], off offset:2112
	global_load_dwordx4 v[112:115], v[12:13], off offset:2144
	v_and_b32_e32 v19, 0xfffff0, v150
	v_lshlrev_b32_e32 v20, 1, v150
	v_lshrrev_b32_e32 v21, 1, v150
	v_and_b32_e32 v23, 3, v150
	v_add_u32_e32 v24, 32, v150
	v_and_b32_e32 v14, 0x70, v35
	v_lshlrev_b32_e32 v18, 7, v148
	v_bfe_u32 v22, v16, 5, 2
	v_and_b32_e32 v33, 0x70, v16
	v_and_or_b32 v16, v20, 8, v19
	v_and_or_b32 v19, v21, 4, v23
	v_and_b32_e32 v20, 0xfffff0, v24
	v_lshlrev_b32_e32 v21, 1, v24
	v_lshl_add_u32 v40, v34, 7, 0
	v_bitop3_b32 v17, v17, v33, 16 bitop3:0x6c
	v_bitop3_b32 v14, v32, v18, v14 bitop3:0xde
	v_lshrrev_b32_e32 v16, 1, v16
	v_lshlrev_b32_e32 v18, 6, v19
	v_and_or_b32 v19, v21, 8, v20
	v_add_u32_e32 v171, v40, v17
	v_or_b32_e32 v16, v16, v22
	v_lshrrev_b32_e32 v17, 1, v19
	v_lshlrev_b32_e32 v15, 4, v35
	v_add_u32_e32 v172, 0, v14
	v_lshlrev_b32_e32 v14, 9, v16
	v_or_b32_e32 v16, v17, v22
	v_and_b32_e32 v15, 48, v15
	v_lshlrev_b32_e32 v12, 9, v16
	v_or3_b32 v14, v14, v18, v15
	v_or3_b32 v12, v12, v18, v15
	v_add_u32_e32 v173, 0, v14
	v_add_u32_e32 v174, 0, v12
	v_bitop3_b32 v20, v146, v33, 32 bitop3:0x36
	v_add_u32_e32 v175, v40, v20
	v_bitop3_b32 v41, v146, v33, 64 bitop3:0x36
	v_add_u32_e32 v176, v40, v41
	v_bitop3_b32 v33, v146, v33, s88 bitop3:0x36
	v_add_u32_e32 v177, v40, v33
	s_waitcnt vmcnt(6)
	ds_write_b128 v172, v[0:3] offset:32768
	s_waitcnt vmcnt(5)
	ds_write_b128 v173, v[4:7]
	s_waitcnt vmcnt(4)
	ds_write_b128 v174, v[8:11]
	s_waitcnt lgkmcnt(0)
	s_barrier
	ds_read_b128 v[0:3], v171 offset:32768
	ds_read_b128 v[16:19], v171 offset:36864
	ds_read_b128 v[36:39], v175 offset:32768
	s_waitcnt vmcnt(3) lgkmcnt(2)
	v_mfma_f32_32x32x16_bf16 v[0:15], v[0:3], v[116:119], 0
	s_waitcnt vmcnt(2) lgkmcnt(0)
	v_mfma_f32_32x32x16_bf16 v[0:15], v[36:39], v[120:123], v[0:15]
	ds_read_b128 v[36:39], v175 offset:36864
	v_mfma_f32_32x32x16_bf16 v[16:31], v[16:19], v[116:119], 0
	s_waitcnt lgkmcnt(0)
	v_mfma_f32_32x32x16_bf16 v[16:31], v[36:39], v[120:123], v[16:31]
	ds_read_b128 v[36:39], v176 offset:32768
	s_waitcnt vmcnt(1) lgkmcnt(0)
	v_mfma_f32_32x32x16_bf16 v[0:15], v[36:39], v[124:127], v[0:15]
	ds_read_b128 v[36:39], v176 offset:36864
	s_waitcnt lgkmcnt(0)
	v_mfma_f32_32x32x16_bf16 v[16:31], v[36:39], v[124:127], v[16:31]
	ds_read_b128 v[36:39], v177 offset:32768
	s_waitcnt vmcnt(0) lgkmcnt(0)
	v_mfma_f32_32x32x16_bf16 v[0:15], v[36:39], v[112:115], v[0:15]
	ds_read_b128 v[36:39], v177 offset:36864
	s_waitcnt lgkmcnt(0)
	v_mfma_f32_32x32x16_bf16 v[16:31], v[36:39], v[112:115], v[16:31]
	s_nop 8
	v_max_f32_e32 v33, v1, v1
	v_max_f32_e32 v36, v0, v0
	v_max_f32_e32 v33, v36, v33
	v_max3_f32 v33, v33, v2, v3
	v_max3_f32 v33, v33, v4, v5
	v_max3_f32 v33, v33, v6, v7
	v_max3_f32 v33, v33, v8, v9
	v_max3_f32 v33, v33, v10, v11
	v_max3_f32 v33, v33, v12, v13
	v_max3_f32 v33, v33, v14, v15
	v_max3_f32 v33, v33, v16, v17
	v_max3_f32 v33, v33, v18, v19
	v_max3_f32 v33, v33, v20, v21
	v_max3_f32 v33, v33, v22, v23
	v_max3_f32 v33, v33, v24, v25
	v_max3_f32 v33, v33, v26, v27
	v_max3_f32 v33, v33, v28, v29
	v_max3_f32 v33, v33, v30, v31
	v_mov_b32_e32 v36, v33
	s_nop 1
	v_permlane32_swap_b32_e32 v33, v36
	v_max_f32_e32 v36, v36, v36
	v_max_f32_e32 v33, v33, v33
	v_max_f32_e32 v33, v33, v36
	v_add_f32_e32 v36, 0x7149f2ca, v33
	v_cmp_ge_f32_e32 vcc, s66, v36
	s_cmp_eq_u64 vcc, exec
	s_cbranch_scc0 .LBB0_865
	v_mov_b32_e32 v144, 0xf149f2ca
	v_mov_b32_e32 v178, 1.0

.LBB0_1065:
	v_mbcnt_lo_u32_b32 v200, -1, 0
	v_mbcnt_hi_u32_b32 v200, -1, v200
	v_and_b32_e32 v201, 15, v200
	v_lshrrev_b32_e32 v182, 2, v200
	v_sub_u32_e32 v201, v182, v201
	v_add_u32_e32 v201, v196, v201
	v_lshrrev_b32_e32 v169, 4, v200
	v_and_b32_e32 v194, 3, v200
	v_sub_u32_e32 v169, v194, v169
	v_lshl_add_u32 v169, v169, 3, v198
	v_lshl_or_b32 v168, s27, 8, v169
	v_lshl_add_u32 v195, v194, 4, v182
	v_lshlrev_b32_e32 v195, 2, v195
	v_xor_b32_e32 v188, 1, v200
	v_lshlrev_b32_e32 v188, 2, v188
	v_xor_b32_e32 v200, 2, v200
	v_lshlrev_b32_e32 v200, 2, v200
	ds_bpermute_b32 v208, v195, v72
	ds_bpermute_b32 v209, v195, v73
	ds_bpermute_b32 v210, v195, v74
	ds_bpermute_b32 v211, v195, v75
	ds_bpermute_b32 v212, v195, v80
	ds_bpermute_b32 v213, v195, v81
	ds_bpermute_b32 v214, v195, v82
	ds_bpermute_b32 v215, v195, v83
	s_waitcnt lgkmcnt(7)
	ds_bpermute_b32 v216, v195, v64
	ds_bpermute_b32 v217, v195, v65
	ds_bpermute_b32 v218, v195, v66
	ds_bpermute_b32 v219, v195, v67
	ds_bpermute_b32 v220, v195, v68
	ds_bpermute_b32 v221, v195, v69
	ds_bpermute_b32 v222, v195, v70
	ds_bpermute_b32 v223, v195, v71
	s_waitcnt lgkmcnt(0)
	v_mov_b64_e32 v[72:73], v[208:209]
	v_mov_b64_e32 v[74:75], v[210:211]
	v_mov_b64_e32 v[80:81], v[212:213]
	v_mov_b64_e32 v[82:83], v[214:215]
	v_mov_b64_e32 v[64:65], v[216:217]
	v_mov_b64_e32 v[66:67], v[218:219]
	v_mov_b64_e32 v[68:69], v[220:221]
	v_mov_b64_e32 v[70:71], v[222:223]
	ds_bpermute_b32 v154, v195, v174
	ds_bpermute_b32 v155, v195, v175
	ds_bpermute_b32 v156, v195, v176
	ds_bpermute_b32 v157, v195, v177
	ds_bpermute_b32 v158, v195, v184
	ds_bpermute_b32 v159, v195, v185
	ds_bpermute_b32 v160, v195, v186
	ds_bpermute_b32 v161, v195, v187
	s_waitcnt lgkmcnt(7)
	ds_bpermute_b32 v162, v195, v170
	ds_bpermute_b32 v163, v195, v171
	ds_bpermute_b32 v164, v195, v172
	ds_bpermute_b32 v165, v195, v173
	ds_bpermute_b32 v224, v195, v178
	ds_bpermute_b32 v225, v195, v179
	ds_bpermute_b32 v226, v195, v180
	ds_bpermute_b32 v227, v195, v181
	s_waitcnt lgkmcnt(0)
	v_mov_b64_e32 v[174:175], v[154:155]
	v_mov_b64_e32 v[176:177], v[156:157]
	v_mov_b64_e32 v[184:185], v[158:159]
	v_mov_b64_e32 v[186:187], v[160:161]
	v_mov_b64_e32 v[170:171], v[162:163]
	v_mov_b64_e32 v[172:173], v[164:165]
	v_mov_b64_e32 v[178:179], v[224:225]
	v_mov_b64_e32 v[180:181], v[226:227]
	ds_bpermute_b32 v154, v195, v124
	ds_bpermute_b32 v155, v195, v125
	ds_bpermute_b32 v156, v195, v126
	ds_bpermute_b32 v157, v195, v127
	ds_bpermute_b32 v158, v195, v120
	ds_bpermute_b32 v159, v195, v121
	ds_bpermute_b32 v160, v195, v122
	ds_bpermute_b32 v161, v195, v123
	s_waitcnt lgkmcnt(7)
	ds_bpermute_b32 v162, v195, v116
	ds_bpermute_b32 v163, v195, v117
	ds_bpermute_b32 v164, v195, v118
	ds_bpermute_b32 v165, v195, v119
	ds_bpermute_b32 v224, v195, v112
	ds_bpermute_b32 v225, v195, v113
	ds_bpermute_b32 v226, v195, v114
	ds_bpermute_b32 v227, v195, v115
	s_lshl_b32 s15, s26, 8
	s_add_i32 s17, s15, 0xffff8000
	s_and_b64 s[22:23], s[22:23], exec
	s_cselect_b32 s17, s15, s17
	s_cselect_b32 s23, s35, s56
	s_cselect_b32 s22, s53, s94
	v_readlane_b32 s100, v253, 59
	s_nop 0
	s_cselect_b32 s25, s75, s100
	v_readlane_b32 s100, v253, 58
	s_nop 0
	s_cselect_b32 s24, s74, s100
	v_readlane_b32 s26, v254, 49
	v_readlane_b32 s27, v254, 50
	v_add_u32_e32 v189, s17, v201
	v_lshl_add_u32 v189, v189, 10, v168
	v_lshlrev_b32_e32 v189, 2, v189
	v_add_u32_e32 v191, s15, v201
	v_lshl_add_u32 v190, v191, 10, v168
	v_lshlrev_b32_e32 v190, 1, v190
	v_lshlrev_b32_e32 v191, 2, v191
	v_cmp_eq_u32_e32 vcc, 0, v194
	s_waitcnt vmcnt(0)
	s_waitcnt lgkmcnt(0)
	ds_bpermute_b32 v208, v195, v140
	ds_bpermute_b32 v209, v195, v141
	ds_bpermute_b32 v210, v195, v142
	ds_bpermute_b32 v211, v195, v143
	ds_bpermute_b32 v212, v195, v136
	ds_bpermute_b32 v213, v195, v137
	ds_bpermute_b32 v214, v195, v138
	ds_bpermute_b32 v215, v195, v139
	s_waitcnt lgkmcnt(7)
	ds_bpermute_b32 v216, v195, v132
	ds_bpermute_b32 v217, v195, v133
	ds_bpermute_b32 v218, v195, v134
	ds_bpermute_b32 v219, v195, v135
	ds_bpermute_b32 v220, v195, v128
	ds_bpermute_b32 v221, v195, v129
	ds_bpermute_b32 v222, v195, v130
	ds_bpermute_b32 v223, v195, v131
	s_waitcnt lgkmcnt(0)
	global_load_dwordx4 v[140:143], v189, s[22:23]
	global_load_dwordx4 v[136:139], v189, s[22:23] offset:16
	global_load_dwordx4 v[132:135], v189, s[22:23] offset:512
	global_load_dwordx4 v[128:131], v189, s[22:23] offset:528
	s_add_u32 s22, s22, 0x10000
	s_addc_u32 s23, s23, 0
	global_load_dwordx4 v[124:127], v189, s[22:23]
	global_load_dwordx4 v[120:123], v189, s[22:23] offset:16
	global_load_dwordx4 v[116:119], v189, s[22:23] offset:512
	global_load_dwordx4 v[112:115], v189, s[22:23] offset:528
	s_add_u32 s22, s22, 0x10000
	s_addc_u32 s23, s23, 0
	s_waitcnt vmcnt(4)
	v_pk_fma_f32 v[140:141], v[208:209], v[72:73], v[140:141]
	v_pk_fma_f32 v[142:143], v[210:211], v[74:75], v[142:143]
	v_pk_fma_f32 v[136:137], v[212:213], v[80:81], v[136:137]
	v_pk_fma_f32 v[138:139], v[214:215], v[82:83], v[138:139]
	v_pk_fma_f32 v[132:133], v[216:217], v[64:65], v[132:133]
	v_pk_fma_f32 v[134:135], v[218:219], v[66:67], v[134:135]
	v_pk_fma_f32 v[128:129], v[220:221], v[68:69], v[128:129]
	v_pk_fma_f32 v[130:131], v[222:223], v[70:71], v[130:131]
	ds_bpermute_b32 v208, v195, v108
	ds_bpermute_b32 v209, v195, v109
	ds_bpermute_b32 v210, v195, v110
	ds_bpermute_b32 v211, v195, v111
	ds_bpermute_b32 v212, v195, v104
	ds_bpermute_b32 v213, v195, v105
	ds_bpermute_b32 v214, v195, v106
	ds_bpermute_b32 v215, v195, v107
	global_store_dwordx4 v189, v[140:143], s[24:25]
	global_store_dwordx4 v189, v[136:139], s[24:25] offset:16
	global_store_dwordx4 v189, v[132:135], s[24:25] offset:512
	global_store_dwordx4 v189, v[128:131], s[24:25] offset:528
	s_add_u32 s24, s24, 0x10000
	s_addc_u32 s25, s25, 0
	s_waitcnt lgkmcnt(6)
	ds_bpermute_b32 v216, v195, v100
	ds_bpermute_b32 v217, v195, v101
	ds_bpermute_b32 v218, v195, v102
	ds_bpermute_b32 v219, v195, v103
	ds_bpermute_b32 v220, v195, v96
	ds_bpermute_b32 v221, v195, v97
	ds_bpermute_b32 v222, v195, v98
	ds_bpermute_b32 v223, v195, v99
	v_pk_mul_f32 v[168:169], v[140:141], v[140:141]
	v_pk_fma_f32 v[168:169], v[142:143], v[142:143], v[168:169]
	v_pk_fma_f32 v[168:169], v[136:137], v[136:137], v[168:169]
	v_pk_fma_f32 v[168:169], v[138:139], v[138:139], v[168:169]
	v_pk_fma_f32 v[168:169], v[132:133], v[132:133], v[168:169]
	v_pk_fma_f32 v[168:169], v[134:135], v[134:135], v[168:169]
	v_pk_fma_f32 v[168:169], v[128:129], v[128:129], v[168:169]
	v_pk_fma_f32 v[168:169], v[130:131], v[130:131], v[168:169]
	v_add_f32_e32 v193, v168, v169
	ds_bpermute_b32 v192, v188, v193
	v_pk_mul_f32 v[140:141], v[174:175], v[140:141]
	v_pk_mul_f32 v[142:143], v[176:177], v[142:143]
	v_pk_mul_f32 v[136:137], v[184:185], v[136:137]
	v_pk_mul_f32 v[138:139], v[186:187], v[138:139]
	v_pk_mul_f32 v[132:133], v[170:171], v[132:133]
	v_pk_mul_f32 v[134:135], v[172:173], v[134:135]
	v_pk_mul_f32 v[128:129], v[178:179], v[128:129]
	v_pk_mul_f32 v[130:131], v[180:181], v[130:131]
	s_waitcnt lgkmcnt(0)
	v_add_f32_e32 v193, v193, v192
	ds_bpermute_b32 v192, v200, v193
	v_cvt_pk_bf16_f32 v140, v140, v141
	v_cvt_pk_bf16_f32 v141, v142, v143
	v_cvt_pk_bf16_f32 v142, v136, v137
	v_cvt_pk_bf16_f32 v143, v138, v139
	v_cvt_pk_bf16_f32 v132, v132, v133
	v_cvt_pk_bf16_f32 v133, v134, v135
	v_cvt_pk_bf16_f32 v134, v128, v129
	v_cvt_pk_bf16_f32 v135, v130, v131
	s_waitcnt lgkmcnt(0)
	v_add_f32_e32 v193, v193, v192
	global_store_dwordx4 v190, v[140:143], s[26:27]
	global_store_dwordx4 v190, v[132:135], s[26:27] offset:256
	s_add_u32 s26, s26, 0x8000
	s_addc_u32 s27, s27, 0
	s_and_saveexec_b64 s[100:101], vcc
	s_cbranch_execz .Lepit_op_na0
	global_atomic_add_f32 v191, v193, s[54:55]

.LBB0_1253:
	v_mbcnt_lo_u32_b32 v227, -1, 0
	v_mbcnt_hi_u32_b32 v227, -1, v227
	v_and_b32_e32 v232, 15, v227
	v_lshrrev_b32_e32 v233, 2, v227
	v_sub_u32_e32 v232, v233, v232
	v_add_u32_e32 v232, v208, v232
	v_lshrrev_b32_e32 v241, 4, v227
	v_and_b32_e32 v240, 3, v227
	v_sub_u32_e32 v241, v240, v241
	v_lshl_add_u32 v241, v241, 3, v211
	v_lshl_or_b32 v241, s9, 8, v241
	v_lshl_add_u32 v222, v240, 4, v233
	v_lshlrev_b32_e32 v222, 2, v222
	v_xor_b32_e32 v226, 1, v227
	v_lshlrev_b32_e32 v226, 2, v226
	v_xor_b32_e32 v227, 2, v227
	v_lshlrev_b32_e32 v227, 2, v227
	ds_bpermute_b32 v144, v222, v136
	ds_bpermute_b32 v145, v222, v137
	ds_bpermute_b32 v146, v222, v138
	ds_bpermute_b32 v147, v222, v139
	ds_bpermute_b32 v148, v222, v140
	ds_bpermute_b32 v149, v222, v141
	ds_bpermute_b32 v150, v222, v142
	ds_bpermute_b32 v151, v222, v143
	s_waitcnt lgkmcnt(7)
	ds_bpermute_b32 v154, v222, v128
	ds_bpermute_b32 v155, v222, v129
	ds_bpermute_b32 v156, v222, v130
	ds_bpermute_b32 v157, v222, v131
	ds_bpermute_b32 v158, v222, v132
	ds_bpermute_b32 v159, v222, v133
	ds_bpermute_b32 v160, v222, v134
	ds_bpermute_b32 v161, v222, v135
	s_waitcnt lgkmcnt(0)
	v_mov_b64_e32 v[136:137], v[144:145]
	v_mov_b64_e32 v[138:139], v[146:147]
	v_mov_b64_e32 v[140:141], v[148:149]
	v_mov_b64_e32 v[142:143], v[150:151]
	v_mov_b64_e32 v[128:129], v[154:155]
	v_mov_b64_e32 v[130:131], v[156:157]
	v_mov_b64_e32 v[132:133], v[158:159]
	v_mov_b64_e32 v[134:135], v[160:161]
	ds_bpermute_b32 v214, v222, v186
	ds_bpermute_b32 v215, v222, v187
	ds_bpermute_b32 v216, v222, v188
	ds_bpermute_b32 v217, v222, v189
	ds_bpermute_b32 v218, v222, v194
	ds_bpermute_b32 v219, v222, v195
	ds_bpermute_b32 v220, v222, v196
	ds_bpermute_b32 v221, v222, v197
	s_waitcnt lgkmcnt(7)
	ds_bpermute_b32 v198, v222, v182
	ds_bpermute_b32 v199, v222, v183
	ds_bpermute_b32 v200, v222, v184
	ds_bpermute_b32 v201, v222, v185
	ds_bpermute_b32 v178, v222, v190
	ds_bpermute_b32 v179, v222, v191
	ds_bpermute_b32 v180, v222, v192
	ds_bpermute_b32 v181, v222, v193
	s_waitcnt lgkmcnt(0)
	v_mov_b64_e32 v[186:187], v[214:215]
	v_mov_b64_e32 v[188:189], v[216:217]
	v_mov_b64_e32 v[194:195], v[218:219]
	v_mov_b64_e32 v[196:197], v[220:221]
	v_mov_b64_e32 v[182:183], v[198:199]
	v_mov_b64_e32 v[184:185], v[200:201]
	v_mov_b64_e32 v[190:191], v[178:179]
	v_mov_b64_e32 v[192:193], v[180:181]
	ds_bpermute_b32 v214, v222, v116
	ds_bpermute_b32 v215, v222, v117
	ds_bpermute_b32 v216, v222, v118
	ds_bpermute_b32 v217, v222, v119
	ds_bpermute_b32 v218, v222, v112
	ds_bpermute_b32 v219, v222, v113
	ds_bpermute_b32 v220, v222, v114
	ds_bpermute_b32 v221, v222, v115
	s_waitcnt lgkmcnt(7)
	ds_bpermute_b32 v198, v222, v92
	ds_bpermute_b32 v199, v222, v93
	ds_bpermute_b32 v200, v222, v94
	ds_bpermute_b32 v201, v222, v95
	ds_bpermute_b32 v178, v222, v84
	ds_bpermute_b32 v179, v222, v85
	ds_bpermute_b32 v180, v222, v86
	ds_bpermute_b32 v181, v222, v87
	s_lshl_b32 s11, s54, 8
	s_add_i32 s13, s11, 0xffff8000
	s_and_b64 s[20:21], s[20:21], exec
	s_cselect_b32 s13, s11, s13
	v_readlane_b32 s100, v253, 59
	s_nop 0
	s_cselect_b32 s21, s75, s100
	v_readlane_b32 s100, v253, 58
	s_nop 0
	s_cselect_b32 s20, s74, s100
	s_mov_b64 s[100:101], s[20:21]
	v_readlane_b32 s22, v254, 49
	v_readlane_b32 s23, v254, 50
	v_readlane_b32 s24, v254, 6
	v_readlane_b32 s25, v254, 7
	v_add_u32_e32 v223, s13, v232
	v_lshl_add_u32 v223, v223, 10, v241
	v_lshlrev_b32_e32 v223, 2, v223
	v_add_u32_e32 v225, s11, v232
	v_lshl_add_u32 v224, v225, 10, v241
	v_lshlrev_b32_e32 v224, 1, v224
	v_lshlrev_b32_e32 v225, 2, v225
	v_cmp_eq_u32_e32 vcc, 0, v240
	s_waitcnt vmcnt(0)
	s_waitcnt lgkmcnt(0)
	ds_bpermute_b32 v144, v222, v124
	ds_bpermute_b32 v145, v222, v125
	ds_bpermute_b32 v146, v222, v126
	ds_bpermute_b32 v147, v222, v127
	ds_bpermute_b32 v148, v222, v120
	ds_bpermute_b32 v149, v222, v121
	ds_bpermute_b32 v150, v222, v122
	ds_bpermute_b32 v151, v222, v123
	s_waitcnt lgkmcnt(7)
	ds_bpermute_b32 v154, v222, v108
	ds_bpermute_b32 v155, v222, v109
	ds_bpermute_b32 v156, v222, v110
	ds_bpermute_b32 v157, v222, v111
	ds_bpermute_b32 v158, v222, v100
	ds_bpermute_b32 v159, v222, v101
	ds_bpermute_b32 v160, v222, v102
	ds_bpermute_b32 v161, v222, v103
	s_waitcnt lgkmcnt(0)
	global_load_dwordx4 v[124:127], v223, s[100:101]
	global_load_dwordx4 v[120:123], v223, s[100:101] offset:16
	global_load_dwordx4 v[108:111], v223, s[100:101] offset:512
	global_load_dwordx4 v[100:103], v223, s[100:101] offset:528
	s_add_u32 s100, s100, 0x10000
	s_addc_u32 s101, s101, 0
	global_load_dwordx4 v[116:119], v223, s[100:101]
	global_load_dwordx4 v[112:115], v223, s[100:101] offset:16
	global_load_dwordx4 v[92:95], v223, s[100:101] offset:512
	global_load_dwordx4 v[84:87], v223, s[100:101] offset:528
	s_add_u32 s100, s100, 0x10000
	s_addc_u32 s101, s101, 0
	s_waitcnt vmcnt(4)
	v_pk_fma_f32 v[124:125], v[144:145], v[136:137], v[124:125]
	v_pk_fma_f32 v[126:127], v[146:147], v[138:139], v[126:127]
	v_pk_fma_f32 v[120:121], v[148:149], v[140:141], v[120:121]
	v_pk_fma_f32 v[122:123], v[150:151], v[142:143], v[122:123]
	v_pk_fma_f32 v[108:109], v[154:155], v[128:129], v[108:109]
	v_pk_fma_f32 v[110:111], v[156:157], v[130:131], v[110:111]
	v_pk_fma_f32 v[100:101], v[158:159], v[132:133], v[100:101]
	v_pk_fma_f32 v[102:103], v[160:161], v[134:135], v[102:103]
	ds_bpermute_b32 v144, v222, v104
	ds_bpermute_b32 v145, v222, v105
	ds_bpermute_b32 v146, v222, v106
	ds_bpermute_b32 v147, v222, v107
	ds_bpermute_b32 v148, v222, v96
	ds_bpermute_b32 v149, v222, v97
	ds_bpermute_b32 v150, v222, v98
	ds_bpermute_b32 v151, v222, v99
	global_store_dwordx4 v223, v[124:127], s[20:21]
	global_store_dwordx4 v223, v[120:123], s[20:21] offset:16
	global_store_dwordx4 v223, v[108:111], s[20:21] offset:512
	global_store_dwordx4 v223, v[100:103], s[20:21] offset:528
	s_add_u32 s20, s20, 0x10000
	s_addc_u32 s21, s21, 0
	s_waitcnt lgkmcnt(6)
	ds_bpermute_b32 v154, v222, v76
	ds_bpermute_b32 v155, v222, v77
	ds_bpermute_b32 v156, v222, v78
	ds_bpermute_b32 v157, v222, v79
	ds_bpermute_b32 v158, v222, v72
	ds_bpermute_b32 v159, v222, v73
	ds_bpermute_b32 v160, v222, v74
	ds_bpermute_b32 v161, v222, v75
	v_pk_mul_f32 v[240:241], v[124:125], v[124:125]
	v_pk_fma_f32 v[240:241], v[126:127], v[126:127], v[240:241]
	v_pk_fma_f32 v[240:241], v[120:121], v[120:121], v[240:241]
	v_pk_fma_f32 v[240:241], v[122:123], v[122:123], v[240:241]
	v_pk_fma_f32 v[240:241], v[108:109], v[108:109], v[240:241]
	v_pk_fma_f32 v[240:241], v[110:111], v[110:111], v[240:241]
	v_pk_fma_f32 v[240:241], v[100:101], v[100:101], v[240:241]
	v_pk_fma_f32 v[240:241], v[102:103], v[102:103], v[240:241]
	v_add_f32_e32 v232, v240, v241
	ds_bpermute_b32 v233, v226, v232
	v_pk_mul_f32 v[124:125], v[186:187], v[124:125]
	v_pk_mul_f32 v[126:127], v[188:189], v[126:127]
	v_pk_mul_f32 v[120:121], v[194:195], v[120:121]
	v_pk_mul_f32 v[122:123], v[196:197], v[122:123]
	v_pk_mul_f32 v[108:109], v[182:183], v[108:109]
	v_pk_mul_f32 v[110:111], v[184:185], v[110:111]
	v_pk_mul_f32 v[100:101], v[190:191], v[100:101]
	v_pk_mul_f32 v[102:103], v[192:193], v[102:103]
	s_waitcnt lgkmcnt(0)
	v_add_f32_e32 v232, v232, v233
	ds_bpermute_b32 v233, v227, v232
	v_cvt_pk_bf16_f32 v124, v124, v125
	v_cvt_pk_bf16_f32 v125, v126, v127
	v_cvt_pk_bf16_f32 v126, v120, v121
	v_cvt_pk_bf16_f32 v127, v122, v123
	v_cvt_pk_bf16_f32 v108, v108, v109
	v_cvt_pk_bf16_f32 v109, v110, v111
	v_cvt_pk_bf16_f32 v110, v100, v101
	v_cvt_pk_bf16_f32 v111, v102, v103
	s_waitcnt lgkmcnt(0)
	v_add_f32_e32 v232, v232, v233
	global_store_dwordx4 v224, v[124:127], s[22:23]
	global_store_dwordx4 v224, v[108:111], s[22:23] offset:256
	s_add_u32 s22, s22, 0x8000
	s_addc_u32 s23, s23, 0
	s_mov_b64 exec, vcc
	s_cbranch_execz .Lepit_d0_na0
	global_atomic_add_f32 v225, v232, s[24:25]
.Lepit_d0_na0:
	s_mov_b64 exec, -1
	s_waitcnt lgkmcnt(0)
	global_load_dwordx4 v[104:107], v223, s[100:101]
	global_load_dwordx4 v[96:99], v223, s[100:101] offset:16
	global_load_dwordx4 v[76:79], v223, s[100:101] offset:512
	global_load_dwordx4 v[72:75], v223, s[100:101] offset:528
	s_add_u32 s100, s100, 0x10000
	s_addc_u32 s101, s101, 0
	s_waitcnt vmcnt(10)
	v_pk_fma_f32 v[116:117], v[214:215], v[136:137], v[116:117]
	v_pk_fma_f32 v[118:119], v[216:217], v[138:139], v[118:119]
	v_pk_fma_f32 v[112:113], v[218:219], v[140:141], v[112:113]
	v_pk_fma_f32 v[114:115], v[220:221], v[142:143], v[114:115]
	v_pk_fma_f32 v[92:93], v[198:199], v[128:129], v[92:93]
	v_pk_fma_f32 v[94:95], v[200:201], v[130:131], v[94:95]
	v_pk_fma_f32 v[84:85], v[178:179], v[132:133], v[84:85]
	v_pk_fma_f32 v[86:87], v[180:181], v[134:135], v[86:87]
	ds_bpermute_b32 v214, v222, v88
	ds_bpermute_b32 v215, v222, v89
	ds_bpermute_b32 v216, v222, v90
	ds_bpermute_b32 v217, v222, v91
	ds_bpermute_b32 v218, v222, v80
	ds_bpermute_b32 v219, v222, v81
	ds_bpermute_b32 v220, v222, v82
	ds_bpermute_b32 v221, v222, v83
	global_store_dwordx4 v223, v[116:119], s[20:21]
	global_store_dwordx4 v223, v[112:115], s[20:21] offset:16
	global_store_dwordx4 v223, v[92:95], s[20:21] offset:512
	global_store_dwordx4 v223, v[84:87], s[20:21] offset:528
	s_add_u32 s20, s20, 0x10000
	s_addc_u32 s21, s21, 0
	s_waitcnt lgkmcnt(6)
	ds_bpermute_b32 v198, v222, v68
	ds_bpermute_b32 v199, v222, v69
	ds_bpermute_b32 v200, v222, v70
	ds_bpermute_b32 v201, v222, v71
	ds_bpermute_b32 v178, v222, v64
	ds_bpermute_b32 v179, v222, v65
	ds_bpermute_b32 v180, v222, v66
	ds_bpermute_b32 v181, v222, v67
	v_pk_mul_f32 v[240:241], v[116:117], v[116:117]
	v_pk_fma_f32 v[240:241], v[118:119], v[118:119], v[240:241]
	v_pk_fma_f32 v[240:241], v[112:113], v[112:113], v[240:241]
	v_pk_fma_f32 v[240:241], v[114:115], v[114:115], v[240:241]
	v_pk_fma_f32 v[240:241], v[92:93], v[92:93], v[240:241]
	v_pk_fma_f32 v[240:241], v[94:95], v[94:95], v[240:241]
	v_pk_fma_f32 v[240:241], v[84:85], v[84:85], v[240:241]
	v_pk_fma_f32 v[240:241], v[86:87], v[86:87], v[240:241]
	v_add_f32_e32 v232, v240, v241
	ds_bpermute_b32 v233, v226, v232
	v_pk_mul_f32 v[116:117], v[186:187], v[116:117]
	v_pk_mul_f32 v[118:119], v[188:189], v[118:119]
	v_pk_mul_f32 v[112:113], v[194:195], v[112:113]
	v_pk_mul_f32 v[114:115], v[196:197], v[114:115]
	v_pk_mul_f32 v[92:93], v[182:183], v[92:93]
	v_pk_mul_f32 v[94:95], v[184:185], v[94:95]
	v_pk_mul_f32 v[84:85], v[190:191], v[84:85]
	v_pk_mul_f32 v[86:87], v[192:193], v[86:87]
	s_waitcnt lgkmcnt(0)
	v_add_f32_e32 v232, v232, v233
	ds_bpermute_b32 v233, v227, v232
	v_cvt_pk_bf16_f32 v116, v116, v117
	v_cvt_pk_bf16_f32 v117, v118, v119
	v_cvt_pk_bf16_f32 v118, v112, v113
	v_cvt_pk_bf16_f32 v119, v114, v115
	v_cvt_pk_bf16_f32 v92, v92, v93
	v_cvt_pk_bf16_f32 v93, v94, v95
	v_cvt_pk_bf16_f32 v94, v84, v85
	v_cvt_pk_bf16_f32 v95, v86, v87
	s_waitcnt lgkmcnt(0)
	v_add_f32_e32 v232, v232, v233
	global_store_dwordx4 v224, v[116:119], s[22:23]
	global_store_dwordx4 v224, v[92:95], s[22:23] offset:256
	s_add_u32 s22, s22, 0x8000
	s_addc_u32 s23, s23, 0
	s_mov_b64 exec, vcc
	s_cbranch_execz .Lepit_d0_na1
	global_atomic_add_f32 v225, v232, s[24:25] offset:64
.Lepit_d0_na1:
	s_mov_b64 exec, -1
	s_waitcnt lgkmcnt(0)
	global_load_dwordx4 v[88:91], v223, s[100:101]
	global_load_dwordx4 v[80:83], v223, s[100:101] offset:16
	global_load_dwordx4 v[68:71], v223, s[100:101] offset:512
	global_load_dwordx4 v[64:67], v223, s[100:101] offset:528
	s_add_u32 s100, s100, 0x50000
	s_addc_u32 s101, s101, 0
	s_waitcnt vmcnt(10)
	v_pk_fma_f32 v[104:105], v[144:145], v[136:137], v[104:105]
	v_pk_fma_f32 v[106:107], v[146:147], v[138:139], v[106:107]
	v_pk_fma_f32 v[96:97], v[148:149], v[140:141], v[96:97]
	v_pk_fma_f32 v[98:99], v[150:151], v[142:143], v[98:99]
	v_pk_fma_f32 v[76:77], v[154:155], v[128:129], v[76:77]
	v_pk_fma_f32 v[78:79], v[156:157], v[130:131], v[78:79]
	v_pk_fma_f32 v[72:73], v[158:159], v[132:133], v[72:73]
	v_pk_fma_f32 v[74:75], v[160:161], v[134:135], v[74:75]
	ds_bpermute_b32 v144, v222, v60
	ds_bpermute_b32 v145, v222, v61
	ds_bpermute_b32 v146, v222, v62
	ds_bpermute_b32 v147, v222, v63
	ds_bpermute_b32 v148, v222, v56
	ds_bpermute_b32 v149, v222, v57
	ds_bpermute_b32 v150, v222, v58
	ds_bpermute_b32 v151, v222, v59
	global_store_dwordx4 v223, v[104:107], s[20:21]
	global_store_dwordx4 v223, v[96:99], s[20:21] offset:16
	global_store_dwordx4 v223, v[76:79], s[20:21] offset:512
	global_store_dwordx4 v223, v[72:75], s[20:21] offset:528
	s_add_u32 s20, s20, 0x10000
	s_addc_u32 s21, s21, 0
	s_waitcnt lgkmcnt(6)
	ds_bpermute_b32 v154, v222, v44
	ds_bpermute_b32 v155, v222, v45
	ds_bpermute_b32 v156, v222, v46
	ds_bpermute_b32 v157, v222, v47
	ds_bpermute_b32 v158, v222, v36
	ds_bpermute_b32 v159, v222, v37
	ds_bpermute_b32 v160, v222, v38
	ds_bpermute_b32 v161, v222, v39
	v_pk_mul_f32 v[240:241], v[104:105], v[104:105]
	v_pk_fma_f32 v[240:241], v[106:107], v[106:107], v[240:241]
	v_pk_fma_f32 v[240:241], v[96:97], v[96:97], v[240:241]
	v_pk_fma_f32 v[240:241], v[98:99], v[98:99], v[240:241]
	v_pk_fma_f32 v[240:241], v[76:77], v[76:77], v[240:241]
	v_pk_fma_f32 v[240:241], v[78:79], v[78:79], v[240:241]
	v_pk_fma_f32 v[240:241], v[72:73], v[72:73], v[240:241]
	v_pk_fma_f32 v[240:241], v[74:75], v[74:75], v[240:241]
	v_add_f32_e32 v232, v240, v241
	ds_bpermute_b32 v233, v226, v232
	v_pk_mul_f32 v[104:105], v[186:187], v[104:105]
	v_pk_mul_f32 v[106:107], v[188:189], v[106:107]
	v_pk_mul_f32 v[96:97], v[194:195], v[96:97]
	v_pk_mul_f32 v[98:99], v[196:197], v[98:99]
	v_pk_mul_f32 v[76:77], v[182:183], v[76:77]
	v_pk_mul_f32 v[78:79], v[184:185], v[78:79]
	v_pk_mul_f32 v[72:73], v[190:191], v[72:73]
	v_pk_mul_f32 v[74:75], v[192:193], v[74:75]
	s_waitcnt lgkmcnt(0)
	v_add_f32_e32 v232, v232, v233
	ds_bpermute_b32 v233, v227, v232
	v_cvt_pk_bf16_f32 v104, v104, v105
	v_cvt_pk_bf16_f32 v105, v106, v107
	v_cvt_pk_bf16_f32 v106, v96, v97
	v_cvt_pk_bf16_f32 v107, v98, v99
	v_cvt_pk_bf16_f32 v76, v76, v77
	v_cvt_pk_bf16_f32 v77, v78, v79
	v_cvt_pk_bf16_f32 v78, v72, v73
	v_cvt_pk_bf16_f32 v79, v74, v75
	s_waitcnt lgkmcnt(0)
	v_add_f32_e32 v232, v232, v233
	global_store_dwordx4 v224, v[104:107], s[22:23]
	global_store_dwordx4 v224, v[76:79], s[22:23] offset:256
	s_add_u32 s22, s22, 0x8000
	s_addc_u32 s23, s23, 0
	s_mov_b64 exec, vcc
	s_cbranch_execz .Lepit_d0_na2
	global_atomic_add_f32 v225, v232, s[24:25] offset:128
.Lepit_d0_na2:
	s_mov_b64 exec, -1
	s_waitcnt lgkmcnt(0)
	global_load_dwordx4 v[60:63], v223, s[100:101]
	global_load_dwordx4 v[56:59], v223, s[100:101] offset:16
	global_load_dwordx4 v[44:47], v223, s[100:101] offset:512
	global_load_dwordx4 v[36:39], v223, s[100:101] offset:528
	s_add_u32 s100, s100, 0x10000
	s_addc_u32 s101, s101, 0
	s_waitcnt vmcnt(10)
	v_pk_fma_f32 v[88:89], v[214:215], v[136:137], v[88:89]
	v_pk_fma_f32 v[90:91], v[216:217], v[138:139], v[90:91]
	v_pk_fma_f32 v[80:81], v[218:219], v[140:141], v[80:81]
	v_pk_fma_f32 v[82:83], v[220:221], v[142:143], v[82:83]
	v_pk_fma_f32 v[68:69], v[198:199], v[128:129], v[68:69]
	v_pk_fma_f32 v[70:71], v[200:201], v[130:131], v[70:71]
	v_pk_fma_f32 v[64:65], v[178:179], v[132:133], v[64:65]
	v_pk_fma_f32 v[66:67], v[180:181], v[134:135], v[66:67]
	ds_bpermute_b32 v214, v222, v52
	ds_bpermute_b32 v215, v222, v53
	ds_bpermute_b32 v216, v222, v54
	ds_bpermute_b32 v217, v222, v55
	ds_bpermute_b32 v218, v222, v48
	ds_bpermute_b32 v219, v222, v49
	ds_bpermute_b32 v220, v222, v50
	ds_bpermute_b32 v221, v222, v51
	global_store_dwordx4 v223, v[88:91], s[20:21]
	global_store_dwordx4 v223, v[80:83], s[20:21] offset:16
	global_store_dwordx4 v223, v[68:71], s[20:21] offset:512
	global_store_dwordx4 v223, v[64:67], s[20:21] offset:528
	s_add_u32 s20, s20, 0x50000
	s_addc_u32 s21, s21, 0
	s_waitcnt lgkmcnt(6)
	ds_bpermute_b32 v198, v222, v28
	ds_bpermute_b32 v199, v222, v29
	ds_bpermute_b32 v200, v222, v30
	ds_bpermute_b32 v201, v222, v31
	ds_bpermute_b32 v178, v222, v20
	ds_bpermute_b32 v179, v222, v21
	ds_bpermute_b32 v180, v222, v22
	ds_bpermute_b32 v181, v222, v23
	v_pk_mul_f32 v[240:241], v[88:89], v[88:89]
	v_pk_fma_f32 v[240:241], v[90:91], v[90:91], v[240:241]
	v_pk_fma_f32 v[240:241], v[80:81], v[80:81], v[240:241]
	v_pk_fma_f32 v[240:241], v[82:83], v[82:83], v[240:241]
	v_pk_fma_f32 v[240:241], v[68:69], v[68:69], v[240:241]
	v_pk_fma_f32 v[240:241], v[70:71], v[70:71], v[240:241]
	v_pk_fma_f32 v[240:241], v[64:65], v[64:65], v[240:241]
	v_pk_fma_f32 v[240:241], v[66:67], v[66:67], v[240:241]
	v_add_f32_e32 v232, v240, v241
	ds_bpermute_b32 v233, v226, v232
	v_pk_mul_f32 v[88:89], v[186:187], v[88:89]
	v_pk_mul_f32 v[90:91], v[188:189], v[90:91]
	v_pk_mul_f32 v[80:81], v[194:195], v[80:81]
	v_pk_mul_f32 v[82:83], v[196:197], v[82:83]
	v_pk_mul_f32 v[68:69], v[182:183], v[68:69]
	v_pk_mul_f32 v[70:71], v[184:185], v[70:71]
	v_pk_mul_f32 v[64:65], v[190:191], v[64:65]
	v_pk_mul_f32 v[66:67], v[192:193], v[66:67]
	s_waitcnt lgkmcnt(0)
	v_add_f32_e32 v232, v232, v233
	ds_bpermute_b32 v233, v227, v232
	v_cvt_pk_bf16_f32 v88, v88, v89
	v_cvt_pk_bf16_f32 v89, v90, v91
	v_cvt_pk_bf16_f32 v90, v80, v81
	v_cvt_pk_bf16_f32 v91, v82, v83
	v_cvt_pk_bf16_f32 v68, v68, v69
	v_cvt_pk_bf16_f32 v69, v70, v71
	v_cvt_pk_bf16_f32 v70, v64, v65
	v_cvt_pk_bf16_f32 v71, v66, v67
	s_waitcnt lgkmcnt(0)
	v_add_f32_e32 v232, v232, v233
	global_store_dwordx4 v224, v[88:91], s[22:23]
	global_store_dwordx4 v224, v[68:71], s[22:23] offset:256
	s_add_u32 s22, s22, 0x28000
	s_addc_u32 s23, s23, 0
	s_mov_b64 exec, vcc
	s_cbranch_execz .Lepit_d0_na3
	global_atomic_add_f32 v225, v232, s[24:25] offset:192
.Lepit_d0_na3:
	s_mov_b64 exec, -1
	s_waitcnt lgkmcnt(0)
	global_load_dwordx4 v[52:55], v223, s[100:101]
	global_load_dwordx4 v[48:51], v223, s[100:101] offset:16
	global_load_dwordx4 v[28:31], v223, s[100:101] offset:512
	global_load_dwordx4 v[20:23], v223, s[100:101] offset:528
	s_add_u32 s100, s100, 0x10000
	s_addc_u32 s101, s101, 0
	s_waitcnt vmcnt(10)
	v_pk_fma_f32 v[60:61], v[144:145], v[136:137], v[60:61]
	v_pk_fma_f32 v[62:63], v[146:147], v[138:139], v[62:63]
	v_pk_fma_f32 v[56:57], v[148:149], v[140:141], v[56:57]
	v_pk_fma_f32 v[58:59], v[150:151], v[142:143], v[58:59]
	v_pk_fma_f32 v[44:45], v[154:155], v[128:129], v[44:45]
	v_pk_fma_f32 v[46:47], v[156:157], v[130:131], v[46:47]
	v_pk_fma_f32 v[36:37], v[158:159], v[132:133], v[36:37]
	v_pk_fma_f32 v[38:39], v[160:161], v[134:135], v[38:39]
	ds_bpermute_b32 v144, v222, v40
	ds_bpermute_b32 v145, v222, v41
	ds_bpermute_b32 v146, v222, v42
	ds_bpermute_b32 v147, v222, v43
	ds_bpermute_b32 v148, v222, v32
	ds_bpermute_b32 v149, v222, v33
	ds_bpermute_b32 v150, v222, v34
	ds_bpermute_b32 v151, v222, v35
	global_store_dwordx4 v223, v[60:63], s[20:21]
	global_store_dwordx4 v223, v[56:59], s[20:21] offset:16
	global_store_dwordx4 v223, v[44:47], s[20:21] offset:512
	global_store_dwordx4 v223, v[36:39], s[20:21] offset:528
	s_add_u32 s20, s20, 0x10000
	s_addc_u32 s21, s21, 0
	s_waitcnt lgkmcnt(6)
	ds_bpermute_b32 v154, v222, v12
	ds_bpermute_b32 v155, v222, v13
	ds_bpermute_b32 v156, v222, v14
	ds_bpermute_b32 v157, v222, v15
	ds_bpermute_b32 v158, v222, v8
	ds_bpermute_b32 v159, v222, v9
	ds_bpermute_b32 v160, v222, v10
	ds_bpermute_b32 v161, v222, v11
	v_pk_mul_f32 v[240:241], v[60:61], v[60:61]
	v_pk_fma_f32 v[240:241], v[62:63], v[62:63], v[240:241]
	v_pk_fma_f32 v[240:241], v[56:57], v[56:57], v[240:241]
	v_pk_fma_f32 v[240:241], v[58:59], v[58:59], v[240:241]
	v_pk_fma_f32 v[240:241], v[44:45], v[44:45], v[240:241]
	v_pk_fma_f32 v[240:241], v[46:47], v[46:47], v[240:241]
	v_pk_fma_f32 v[240:241], v[36:37], v[36:37], v[240:241]
	v_pk_fma_f32 v[240:241], v[38:39], v[38:39], v[240:241]
	v_add_f32_e32 v232, v240, v241
	ds_bpermute_b32 v233, v226, v232
	v_pk_mul_f32 v[60:61], v[186:187], v[60:61]
	v_pk_mul_f32 v[62:63], v[188:189], v[62:63]
	v_pk_mul_f32 v[56:57], v[194:195], v[56:57]
	v_pk_mul_f32 v[58:59], v[196:197], v[58:59]
	v_pk_mul_f32 v[44:45], v[182:183], v[44:45]
	v_pk_mul_f32 v[46:47], v[184:185], v[46:47]
	v_pk_mul_f32 v[36:37], v[190:191], v[36:37]
	v_pk_mul_f32 v[38:39], v[192:193], v[38:39]
	s_waitcnt lgkmcnt(0)
	v_add_f32_e32 v232, v232, v233
	ds_bpermute_b32 v233, v227, v232
	v_cvt_pk_bf16_f32 v60, v60, v61
	v_cvt_pk_bf16_f32 v61, v62, v63
	v_cvt_pk_bf16_f32 v62, v56, v57
	v_cvt_pk_bf16_f32 v63, v58, v59
	v_cvt_pk_bf16_f32 v44, v44, v45
	v_cvt_pk_bf16_f32 v45, v46, v47
	v_cvt_pk_bf16_f32 v46, v36, v37
	v_cvt_pk_bf16_f32 v47, v38, v39
	s_waitcnt lgkmcnt(0)
	v_add_f32_e32 v232, v232, v233
	global_store_dwordx4 v224, v[60:63], s[22:23]
	global_store_dwordx4 v224, v[44:47], s[22:23] offset:256
	s_add_u32 s22, s22, 0x8000
	s_addc_u32 s23, s23, 0
	s_mov_b64 exec, vcc
	s_cbranch_execz .Lepit_d0_na4
	global_atomic_add_f32 v225, v232, s[24:25] offset:512
.Lepit_d0_na4:
	s_mov_b64 exec, -1
	s_waitcnt lgkmcnt(0)
	global_load_dwordx4 v[40:43], v223, s[100:101]
	global_load_dwordx4 v[32:35], v223, s[100:101] offset:16
	global_load_dwordx4 v[12:15], v223, s[100:101] offset:512
	global_load_dwordx4 v[8:11], v223, s[100:101] offset:528
	s_add_u32 s100, s100, 0x10000
	s_addc_u32 s101, s101, 0
	s_waitcnt vmcnt(10)
	v_pk_fma_f32 v[52:53], v[214:215], v[136:137], v[52:53]
	v_pk_fma_f32 v[54:55], v[216:217], v[138:139], v[54:55]
	v_pk_fma_f32 v[48:49], v[218:219], v[140:141], v[48:49]
	v_pk_fma_f32 v[50:51], v[220:221], v[142:143], v[50:51]
	v_pk_fma_f32 v[28:29], v[198:199], v[128:129], v[28:29]
	v_pk_fma_f32 v[30:31], v[200:201], v[130:131], v[30:31]
	v_pk_fma_f32 v[20:21], v[178:179], v[132:133], v[20:21]
	v_pk_fma_f32 v[22:23], v[180:181], v[134:135], v[22:23]
	ds_bpermute_b32 v214, v222, v24
	ds_bpermute_b32 v215, v222, v25
	ds_bpermute_b32 v216, v222, v26
	ds_bpermute_b32 v217, v222, v27
	ds_bpermute_b32 v218, v222, v16
	ds_bpermute_b32 v219, v222, v17
	ds_bpermute_b32 v220, v222, v18
	ds_bpermute_b32 v221, v222, v19
	global_store_dwordx4 v223, v[52:55], s[20:21]
	global_store_dwordx4 v223, v[48:51], s[20:21] offset:16
	global_store_dwordx4 v223, v[28:31], s[20:21] offset:512
	global_store_dwordx4 v223, v[20:23], s[20:21] offset:528
	s_add_u32 s20, s20, 0x10000
	s_addc_u32 s21, s21, 0
	s_waitcnt lgkmcnt(6)
	ds_bpermute_b32 v198, v222, v4
	ds_bpermute_b32 v199, v222, v5
	ds_bpermute_b32 v200, v222, v6
	ds_bpermute_b32 v201, v222, v7
	ds_bpermute_b32 v178, v222, v0
	ds_bpermute_b32 v179, v222, v1
	ds_bpermute_b32 v180, v222, v2
	ds_bpermute_b32 v181, v222, v3
	v_pk_mul_f32 v[240:241], v[52:53], v[52:53]
	v_pk_fma_f32 v[240:241], v[54:55], v[54:55], v[240:241]
	v_pk_fma_f32 v[240:241], v[48:49], v[48:49], v[240:241]
	v_pk_fma_f32 v[240:241], v[50:51], v[50:51], v[240:241]
	v_pk_fma_f32 v[240:241], v[28:29], v[28:29], v[240:241]
	v_pk_fma_f32 v[240:241], v[30:31], v[30:31], v[240:241]
	v_pk_fma_f32 v[240:241], v[20:21], v[20:21], v[240:241]
	v_pk_fma_f32 v[240:241], v[22:23], v[22:23], v[240:241]
	v_add_f32_e32 v232, v240, v241
	ds_bpermute_b32 v233, v226, v232
	v_pk_mul_f32 v[52:53], v[186:187], v[52:53]
	v_pk_mul_f32 v[54:55], v[188:189], v[54:55]
	v_pk_mul_f32 v[48:49], v[194:195], v[48:49]
	v_pk_mul_f32 v[50:51], v[196:197], v[50:51]
	v_pk_mul_f32 v[28:29], v[182:183], v[28:29]
	v_pk_mul_f32 v[30:31], v[184:185], v[30:31]
	v_pk_mul_f32 v[20:21], v[190:191], v[20:21]
	v_pk_mul_f32 v[22:23], v[192:193], v[22:23]
	s_waitcnt lgkmcnt(0)
	v_add_f32_e32 v232, v232, v233
	ds_bpermute_b32 v233, v227, v232
	v_cvt_pk_bf16_f32 v52, v52, v53
	v_cvt_pk_bf16_f32 v53, v54, v55
	v_cvt_pk_bf16_f32 v54, v48, v49
	v_cvt_pk_bf16_f32 v55, v50, v51
	v_cvt_pk_bf16_f32 v28, v28, v29
	v_cvt_pk_bf16_f32 v29, v30, v31
	v_cvt_pk_bf16_f32 v30, v20, v21
	v_cvt_pk_bf16_f32 v31, v22, v23
	s_waitcnt lgkmcnt(0)
	v_add_f32_e32 v232, v232, v233
	global_store_dwordx4 v224, v[52:55], s[22:23]
	global_store_dwordx4 v224, v[28:31], s[22:23] offset:256
	s_add_u32 s22, s22, 0x8000
	s_addc_u32 s23, s23, 0
	s_mov_b64 exec, vcc
	s_cbranch_execz .Lepit_d0_na5
	global_atomic_add_f32 v225, v232, s[24:25] offset:576
.Lepit_d0_na5:
	s_mov_b64 exec, -1
	s_waitcnt lgkmcnt(0)
	global_load_dwordx4 v[24:27], v223, s[100:101]
	global_load_dwordx4 v[16:19], v223, s[100:101] offset:16
	global_load_dwordx4 v[4:7], v223, s[100:101] offset:512
	global_load_dwordx4 v[0:3], v223, s[100:101] offset:528
	s_waitcnt vmcnt(10)
	v_pk_fma_f32 v[40:41], v[144:145], v[136:137], v[40:41]
	v_pk_fma_f32 v[42:43], v[146:147], v[138:139], v[42:43]
	v_pk_fma_f32 v[32:33], v[148:149], v[140:141], v[32:33]
	v_pk_fma_f32 v[34:35], v[150:151], v[142:143], v[34:35]
	v_pk_fma_f32 v[12:13], v[154:155], v[128:129], v[12:13]
	v_pk_fma_f32 v[14:15], v[156:157], v[130:131], v[14:15]
	v_pk_fma_f32 v[8:9], v[158:159], v[132:133], v[8:9]
	v_pk_fma_f32 v[10:11], v[160:161], v[134:135], v[10:11]
	global_store_dwordx4 v223, v[40:43], s[20:21]
	global_store_dwordx4 v223, v[32:35], s[20:21] offset:16
	global_store_dwordx4 v223, v[12:15], s[20:21] offset:512
	global_store_dwordx4 v223, v[8:11], s[20:21] offset:528
	s_add_u32 s20, s20, 0x10000
	s_addc_u32 s21, s21, 0
	v_pk_mul_f32 v[240:241], v[40:41], v[40:41]
	v_pk_fma_f32 v[240:241], v[42:43], v[42:43], v[240:241]
	v_pk_fma_f32 v[240:241], v[32:33], v[32:33], v[240:241]
	v_pk_fma_f32 v[240:241], v[34:35], v[34:35], v[240:241]
	v_pk_fma_f32 v[240:241], v[12:13], v[12:13], v[240:241]
	v_pk_fma_f32 v[240:241], v[14:15], v[14:15], v[240:241]
	v_pk_fma_f32 v[240:241], v[8:9], v[8:9], v[240:241]
	v_pk_fma_f32 v[240:241], v[10:11], v[10:11], v[240:241]
	v_add_f32_e32 v232, v240, v241
	ds_bpermute_b32 v233, v226, v232
	v_pk_mul_f32 v[40:41], v[186:187], v[40:41]
	v_pk_mul_f32 v[42:43], v[188:189], v[42:43]
	v_pk_mul_f32 v[32:33], v[194:195], v[32:33]
	v_pk_mul_f32 v[34:35], v[196:197], v[34:35]
	v_pk_mul_f32 v[12:13], v[182:183], v[12:13]
	v_pk_mul_f32 v[14:15], v[184:185], v[14:15]
	v_pk_mul_f32 v[8:9], v[190:191], v[8:9]
	v_pk_mul_f32 v[10:11], v[192:193], v[10:11]
	s_waitcnt lgkmcnt(0)
	v_add_f32_e32 v232, v232, v233
	ds_bpermute_b32 v233, v227, v232
	v_cvt_pk_bf16_f32 v40, v40, v41
	v_cvt_pk_bf16_f32 v41, v42, v43
	v_cvt_pk_bf16_f32 v42, v32, v33
	v_cvt_pk_bf16_f32 v43, v34, v35
	v_cvt_pk_bf16_f32 v12, v12, v13
	v_cvt_pk_bf16_f32 v13, v14, v15
	v_cvt_pk_bf16_f32 v14, v8, v9
	v_cvt_pk_bf16_f32 v15, v10, v11
	s_waitcnt lgkmcnt(0)
	v_add_f32_e32 v232, v232, v233
	global_store_dwordx4 v224, v[40:43], s[22:23]
	global_store_dwordx4 v224, v[12:15], s[22:23] offset:256
	s_add_u32 s22, s22, 0x8000
	s_addc_u32 s23, s23, 0
	s_mov_b64 exec, vcc
	s_cbranch_execz .Lepit_d0_na6
	global_atomic_add_f32 v225, v232, s[24:25] offset:640
.Lepit_d0_na6:
	s_mov_b64 exec, -1
	s_waitcnt vmcnt(6)
	v_pk_fma_f32 v[24:25], v[214:215], v[136:137], v[24:25]
	v_pk_fma_f32 v[26:27], v[216:217], v[138:139], v[26:27]
	v_pk_fma_f32 v[16:17], v[218:219], v[140:141], v[16:17]
	v_pk_fma_f32 v[18:19], v[220:221], v[142:143], v[18:19]
	v_pk_fma_f32 v[4:5], v[198:199], v[128:129], v[4:5]
	v_pk_fma_f32 v[6:7], v[200:201], v[130:131], v[6:7]
	v_pk_fma_f32 v[0:1], v[178:179], v[132:133], v[0:1]
	v_pk_fma_f32 v[2:3], v[180:181], v[134:135], v[2:3]
	global_store_dwordx4 v223, v[24:27], s[20:21]
	global_store_dwordx4 v223, v[16:19], s[20:21] offset:16
	global_store_dwordx4 v223, v[4:7], s[20:21] offset:512
	global_store_dwordx4 v223, v[0:3], s[20:21] offset:528
	v_pk_mul_f32 v[240:241], v[24:25], v[24:25]
	v_pk_fma_f32 v[240:241], v[26:27], v[26:27], v[240:241]
	v_pk_fma_f32 v[240:241], v[16:17], v[16:17], v[240:241]
	v_pk_fma_f32 v[240:241], v[18:19], v[18:19], v[240:241]
	v_pk_fma_f32 v[240:241], v[4:5], v[4:5], v[240:241]
	v_pk_fma_f32 v[240:241], v[6:7], v[6:7], v[240:241]
	v_pk_fma_f32 v[240:241], v[0:1], v[0:1], v[240:241]
	v_pk_fma_f32 v[240:241], v[2:3], v[2:3], v[240:241]
	v_add_f32_e32 v232, v240, v241
	ds_bpermute_b32 v233, v226, v232
	v_pk_mul_f32 v[24:25], v[186:187], v[24:25]
	v_pk_mul_f32 v[26:27], v[188:189], v[26:27]
	v_pk_mul_f32 v[16:17], v[194:195], v[16:17]
	v_pk_mul_f32 v[18:19], v[196:197], v[18:19]
	v_pk_mul_f32 v[4:5], v[182:183], v[4:5]
	v_pk_mul_f32 v[6:7], v[184:185], v[6:7]
	v_pk_mul_f32 v[0:1], v[190:191], v[0:1]
	v_pk_mul_f32 v[2:3], v[192:193], v[2:3]
	s_waitcnt lgkmcnt(0)
	v_add_f32_e32 v232, v232, v233
	ds_bpermute_b32 v233, v227, v232
	v_cvt_pk_bf16_f32 v24, v24, v25
	v_cvt_pk_bf16_f32 v25, v26, v27
	v_cvt_pk_bf16_f32 v26, v16, v17
	v_cvt_pk_bf16_f32 v27, v18, v19
	v_cvt_pk_bf16_f32 v4, v4, v5
	v_cvt_pk_bf16_f32 v5, v6, v7
	v_cvt_pk_bf16_f32 v6, v0, v1
	v_cvt_pk_bf16_f32 v7, v2, v3
	s_waitcnt lgkmcnt(0)
	v_add_f32_e32 v232, v232, v233
	global_store_dwordx4 v224, v[24:27], s[22:23]
	global_store_dwordx4 v224, v[4:7], s[22:23] offset:256
	s_mov_b64 exec, vcc
	s_cbranch_execz .Lepit_d0_na7
	global_atomic_add_f32 v225, v232, s[24:25] offset:704
.Lepit_d0_na7:
	s_mov_b64 exec, -1

.LBB0_1295:
	s_andn2_b64 vcc, exec, s[4:5]
	s_cbranch_vccnz .LBB0_1230
	s_barrier
	s_branch .LBB0_1230
.LBB0_1305:
	v_readlane_b32 s30, v253, 8
	v_readlane_b32 s31, v253, 9
	s_mov_b32 s35, s89
	s_waitcnt vmcnt(0)
	s_barrier
	s_waitcnt vmcnt(0)
	s_waitcnt vmcnt(0) lgkmcnt(0)
	s_barrier
	v_mbcnt_lo_u32_b32 v0, -1, 0
	v_mbcnt_hi_u32_b32 v0, -1, v0
	s_nop 0
	v_sub_u32_e32 v0, 0, v0
	v_cmp_eq_u32_e32 vcc, s33, v0
	s_and_saveexec_b64 s[46:47], vcc
	s_cbranch_execz .LBB0_1349
	v_readlane_b32 s0, v255, 24
	s_waitcnt vmcnt(0) expcnt(0) lgkmcnt(0)
	s_nop 0
	v_mov_b32_e32 v0, s0
	ds_read_b32 v2, v0
	v_readlane_b32 s0, v255, 25
	s_waitcnt lgkmcnt(0)
	v_cmp_ne_u32_e32 vcc, 0, v2
	v_mov_b32_e32 v0, s0
	ds_read_b32 v0, v0
	s_cbranch_vccnz .LBB0_1320
	s_add_u32 s0, s30, 0x1000
	s_addc_u32 s1, s31, 0
	s_add_u32 s2, s30, 0x1100
	s_addc_u32 s3, s31, 0
	s_add_u32 s4, s30, 0x1200
	s_addc_u32 s5, s31, 0
	s_add_u32 s6, s30, 0x1300
	s_addc_u32 s7, s31, 0
	s_mov_b32 s26, 1
	s_mov_b64 s[8:9], 0
	s_branch .LBB0_1310
